# scan compute loop regenerated by hand: 3 rotating operand sets, full-pair LDS prefetch, pair-trick d1/e2 reduce with DPP-fused broadcast; attention flags via ds ops
# baseline (speedup 1.0000x reference)
; __device__ __forceinline__ float dot4(const f32x4& a, const f32x4& b) {
;     f32x2 t = __builtin_shufflevector(a, a, 0, 1) * __builtin_shufflevector(b, b, 0, 1);
;     t = __builtin_shufflevector(a, a, 2, 3) * __builtin_shufflevector(b, b, 2, 3) + t;
;     return t[0] + t[1];
; }
; __device__ __forceinline__ void scan_unit(const Params& p, int unit) {
;     ...
;         for (int c = 0; c < SC_NC; ++c) {
;             const float* buf = (const float*)(smem + (c & 1) * SC_BUF);
;             float* yb = (float*)(smem + SC_YOFF + (c & 1) * SC_YBUF);
;             const float* bp = buf + sub * 4;
;     ...
;             f32x4 r1 = SC_LD(0, 0), w1 = SC_LD(1, 0), k1 = SC_LD(2, 0), q1 = SC_LD(3, 0), n1 = SC_LD(4, 0);
;             f32x4 r2 = SC_LD(0, 1), w2 = SC_LD(1, 1), k2 = SC_LD(2, 1), g2 = SC_LD(3, 1), n2 = SC_LD(4, 1);
;             float v1 = buf[SC_VOFF + rl], v2 = buf[SC_VOFF + 16 + rl];
;             f32x2 cf = *(const f32x2*)(buf + SC_COFF);
; #pragma unroll
;             for (int pr = 0; pr < SC_TC / 2; ++pr) {
;                 const int sn = 2 * pr + 2;
;                 const f32x4 r1n = SC_LD(0, sn), w1n = SC_LD(1, sn), k1n = SC_LD(2, sn), q1n = SC_LD(3, sn), n1n = SC_LD(4, sn);
;                 const f32x4 r2n = SC_LD(0, sn + 1), w2n = SC_LD(1, sn + 1), k2n = SC_LD(2, sn + 1), g2n = SC_LD(3, sn + 1), n2n = SC_LD(4, sn + 1);
;                 const float v1n = buf[SC_VOFF + sn * 16 + rl], v2n = buf[SC_VOFF + (sn + 1) * 16 + rl];
;                 const f32x2 cfn = *(const f32x2*)(buf + SC_COFF + (pr + 1) * 2);
;                 __builtin_amdgcn_sched_barrier(0x7);
;                 float d1 = dot4(S, q1), e2 = dot4(S, g2);
;                 const f32x4 t1 = S * w1 + v1 * k1;
;                 reduce16x2(d1, e2);
;                 const float d2 = e2 + v1 * cf[0] - d1 * cf[1];
;                 const f32x4 S1 = t1 + d1 * n1;
;                 const f32x4 S2 = (S1 * w2 + v2 * k2) + d2 * n2;
;                 float y1 = dot4(S1, r1), y2 = dot4(S2, r2);
;                 y1 += dppf<0xB1>(y1); y2 += dppf<0xB1>(y2);
;                 float yz = odd_lane ? y2 : y1;
;                 yz += dppf<0x122>(yz); yz += dppf<0x124>(yz); yz += dppf<0x128>(yz);
;                 yb[(2 * pr) * 16 + yoff] = yz;
;                 S = S2;
;                 r1 = r1n; w1 = w1n; k1 = k1n; q1 = q1n; n1 = n1n; r2 = r2n; w2 = w2n; k2 = k2n; g2 = g2n; n2 = n2n; v1 = v1n; v2 = v2n; cf = cfn;
.LBB0_786:
	s_and_b32 s5, s4, 1
	s_mul_i32 s6, s5, 0xa880
	v_lshl_add_u32 v6, s5, 11, v5
	s_add_i32 s5, s6, 0
	v_lshl_add_u32 v9, v169, 2, s5
	v_mov_b32_e32 v7, s5
	v_lshl_add_u32 v8, v4, 2, s5
	v_add_u32_e32 v129, 0xa000, v9
	v_add_u32_e32 v126, 0xa400, v9
	ds_read_b128 v[10:13], v8 offset:24576
	ds_read_b128 v[14:17], v8 offset:24832
	ds_read_b128 v[18:21], v8 offset:16384
	ds_read2_b32 v[50:51], v129 offset0:0 offset1:16
	ds_read_b128 v[22:25], v8 offset:8192
	ds_read_b64 v[52:53], v7 offset:43008
	ds_read_b128 v[26:29], v8 offset:16640
	ds_read_b128 v[30:33], v8 offset:32768
	ds_read_b128 v[34:37], v8 offset:8448
	ds_read_b128 v[38:41], v8 offset:33024
	ds_read_b128 v[42:45], v8 offset:0
	ds_read_b128 v[46:49], v8 offset:256
	ds_read_b128 v[54:57], v8 offset:25088
	ds_read_b128 v[58:61], v8 offset:25344
	ds_read_b128 v[62:65], v8 offset:16896
	ds_read2_b32 v[94:95], v129 offset0:32 offset1:48
	ds_read_b128 v[66:69], v8 offset:8704
	ds_read_b64 v[96:97], v7 offset:43016
	ds_read_b128 v[70:73], v8 offset:17152
	ds_read_b128 v[74:77], v8 offset:33280
	ds_read_b128 v[78:81], v8 offset:8960
	ds_read_b128 v[82:85], v8 offset:33536
	ds_read_b128 v[86:89], v8 offset:512
	ds_read_b128 v[90:93], v8 offset:768
	s_waitcnt lgkmcnt(15)
	v_pk_mul_f32 v[98:99], v[2:3], v[12:13]
	v_pk_mul_f32 v[100:101], v[2:3], v[16:17]
	v_pk_fma_f32 v[98:99], v[0:1], v[10:11], v[98:99]
	v_pk_fma_f32 v[100:101], v[0:1], v[14:15], v[100:101]
	v_add_f32_e32 v106, v98, v99
	v_add_f32_e32 v107, v100, v101
	v_pk_mul_f32 v[102:103], v[18:19], v[50:51] op_sel_hi:[1,0]
	v_pk_mul_f32 v[104:105], v[20:21], v[50:51] op_sel_hi:[1,0]
	v_add_f32_dpp v106, v106, v106 quad_perm:[1,0,3,2] row_mask:0xf bank_mask:0xf bound_ctrl:1
	v_add_f32_dpp v107, v107, v107 quad_perm:[1,0,3,2] row_mask:0xf bank_mask:0xf bound_ctrl:1
	v_pk_fma_f32 v[102:103], v[0:1], v[22:23], v[102:103]
	v_pk_fma_f32 v[104:105], v[2:3], v[24:25], v[104:105]
	v_cndmask_b32_e32 v109, v107, v106, vcc
	v_mul_f32_e32 v108, v50, v52
	v_pk_mul_f32 v[110:111], v[26:27], v[50:51] op_sel:[0,1]
	v_add_f32_dpp v109, v109, v109 row_ror:2 row_mask:0xf bank_mask:0xf bound_ctrl:1
	v_pk_mul_f32 v[112:113], v[28:29], v[50:51] op_sel:[0,1]
	s_nop 0
	v_add_f32_dpp v109, v109, v109 row_ror:4 row_mask:0xf bank_mask:0xf bound_ctrl:1
	s_nop 0
	s_nop 0
	v_add_f32_dpp v109, v109, v109 row_ror:8 row_mask:0xf bank_mask:0xf bound_ctrl:1
	s_nop 0
	s_nop 0
	v_fmac_f32_dpp v102, v109, v30 quad_perm:[0,0,2,2] row_mask:0xf bank_mask:0xf bound_ctrl:1
	v_fmac_f32_dpp v103, v109, v31 quad_perm:[0,0,2,2] row_mask:0xf bank_mask:0xf bound_ctrl:1
	v_fmac_f32_dpp v104, v109, v32 quad_perm:[0,0,2,2] row_mask:0xf bank_mask:0xf bound_ctrl:1
	v_fmac_f32_dpp v105, v109, v33 quad_perm:[0,0,2,2] row_mask:0xf bank_mask:0xf bound_ctrl:1
	v_fmac_f32_dpp v108, v109, -v53 quad_perm:[0,0,2,2] row_mask:0xf bank_mask:0xf bound_ctrl:1
	v_pk_fma_f32 v[110:111], v[102:103], v[34:35], v[110:111]
	v_pk_fma_f32 v[112:113], v[104:105], v[36:37], v[112:113]
	v_add_f32_dpp v108, v109, v108 quad_perm:[1,1,3,3] row_mask:0xf bank_mask:0xf bound_ctrl:1
	s_waitcnt lgkmcnt(14)
	v_pk_fma_f32 v[0:1], v[38:39], v[108:109], v[110:111] op_sel_hi:[1,0,1]
	v_pk_fma_f32 v[2:3], v[40:41], v[108:109], v[112:113] op_sel_hi:[1,0,1]
	ds_read_b128 v[178:181], v8 offset:25600
	ds_read_b128 v[182:185], v8 offset:25856
	ds_read_b128 v[186:189], v8 offset:17408
	ds_read2_b32 v[218:219], v129 offset0:64 offset1:80
	ds_read_b128 v[190:193], v8 offset:9216
	ds_read_b64 v[220:221], v7 offset:43024
	ds_read_b128 v[194:197], v8 offset:17664
	ds_read_b128 v[198:201], v8 offset:33792
	ds_read_b128 v[202:205], v8 offset:9472
	ds_read_b128 v[206:209], v8 offset:34048
	ds_read_b128 v[210:213], v8 offset:1024
	ds_read_b128 v[214:217], v8 offset:1280
	s_waitcnt lgkmcnt(15)
	v_pk_mul_f32 v[118:119], v[104:105], v[44:45]
	v_pk_mul_f32 v[120:121], v[2:3], v[48:49]
	v_pk_fma_f32 v[118:119], v[102:103], v[42:43], v[118:119]
	v_pk_fma_f32 v[120:121], v[0:1], v[46:47], v[120:121]
	v_add_f32_e32 v122, v118, v119
	v_add_f32_e32 v123, v120, v121
	v_pk_mul_f32 v[98:99], v[2:3], v[56:57]
	v_pk_mul_f32 v[100:101], v[2:3], v[60:61]
	v_pk_fma_f32 v[98:99], v[0:1], v[54:55], v[98:99]
	v_pk_fma_f32 v[100:101], v[0:1], v[58:59], v[100:101]
	v_add_f32_e32 v106, v98, v99
	v_add_f32_e32 v107, v100, v101
	v_pk_mul_f32 v[114:115], v[62:63], v[94:95] op_sel_hi:[1,0]
	v_pk_mul_f32 v[116:117], v[64:65], v[94:95] op_sel_hi:[1,0]
	v_add_f32_dpp v106, v106, v106 quad_perm:[1,0,3,2] row_mask:0xf bank_mask:0xf bound_ctrl:1
	v_add_f32_dpp v107, v107, v107 quad_perm:[1,0,3,2] row_mask:0xf bank_mask:0xf bound_ctrl:1
	v_pk_fma_f32 v[114:115], v[0:1], v[66:67], v[114:115]
	v_pk_fma_f32 v[116:117], v[2:3], v[68:69], v[116:117]
	v_cndmask_b32_e32 v109, v107, v106, vcc
	v_mul_f32_e32 v108, v94, v96
	v_pk_mul_f32 v[110:111], v[70:71], v[94:95] op_sel:[0,1]
	v_add_f32_dpp v109, v109, v109 row_ror:2 row_mask:0xf bank_mask:0xf bound_ctrl:1
	v_pk_mul_f32 v[112:113], v[72:73], v[94:95] op_sel:[0,1]
	v_add_f32_dpp v122, v122, v122 quad_perm:[1,0,3,2] row_mask:0xf bank_mask:0xf bound_ctrl:1
	v_add_f32_dpp v109, v109, v109 row_ror:4 row_mask:0xf bank_mask:0xf bound_ctrl:1
	v_add_f32_dpp v123, v123, v123 quad_perm:[1,0,3,2] row_mask:0xf bank_mask:0xf bound_ctrl:1
	v_cndmask_b32_e32 v124, v123, v122, vcc
	v_add_f32_dpp v109, v109, v109 row_ror:8 row_mask:0xf bank_mask:0xf bound_ctrl:1
	s_nop 0
	v_add_f32_dpp v124, v124, v124 row_ror:2 row_mask:0xf bank_mask:0xf bound_ctrl:1
	v_fmac_f32_dpp v114, v109, v74 quad_perm:[0,0,2,2] row_mask:0xf bank_mask:0xf bound_ctrl:1
	v_fmac_f32_dpp v115, v109, v75 quad_perm:[0,0,2,2] row_mask:0xf bank_mask:0xf bound_ctrl:1
	v_fmac_f32_dpp v116, v109, v76 quad_perm:[0,0,2,2] row_mask:0xf bank_mask:0xf bound_ctrl:1
	v_fmac_f32_dpp v117, v109, v77 quad_perm:[0,0,2,2] row_mask:0xf bank_mask:0xf bound_ctrl:1
	v_fmac_f32_dpp v108, v109, -v97 quad_perm:[0,0,2,2] row_mask:0xf bank_mask:0xf bound_ctrl:1
	v_pk_fma_f32 v[110:111], v[114:115], v[78:79], v[110:111]
	v_pk_fma_f32 v[112:113], v[116:117], v[80:81], v[112:113]
	v_add_f32_dpp v108, v109, v108 quad_perm:[1,1,3,3] row_mask:0xf bank_mask:0xf bound_ctrl:1
	s_waitcnt lgkmcnt(14)
; template <int CTRL> __device__ __forceinline__ float dppf(float x) { return __builtin_bit_cast(float, __builtin_amdgcn_mov_dpp(__builtin_bit_cast(int, x), CTRL, 0xf, 0xf, true)); }
; __device__ __forceinline__ float dot4(const f32x4& a, const f32x4& b) {
;     f32x2 t = __builtin_shufflevector(a, a, 0, 1) * __builtin_shufflevector(b, b, 0, 1);
;     t = __builtin_shufflevector(a, a, 2, 3) * __builtin_shufflevector(b, b, 2, 3) + t;
;     return t[0] + t[1];
; }
; __device__ __forceinline__ void reduce16x2(float& a, float& b) {
;     a += dppf<0xB1>(a); b += dppf<0xB1>(b); a += dppf<0x4E>(a); b += dppf<0x4E>(b);
;     a += dppf<0x141>(a); b += dppf<0x141>(b); a += dppf<0x140>(a); b += dppf<0x140>(b);
; }
; __device__ __forceinline__ void scan_unit(const Params& p, int unit) {
;     ...
;             for (int pr = 0; pr < SC_TC / 2; ++pr) {
;                 const int sn = 2 * pr + 2;
;                 const f32x4 r1n = SC_LD(0, sn), w1n = SC_LD(1, sn), k1n = SC_LD(2, sn), q1n = SC_LD(3, sn), n1n = SC_LD(4, sn);
;                 const f32x4 r2n = SC_LD(0, sn + 1), w2n = SC_LD(1, sn + 1), k2n = SC_LD(2, sn + 1), g2n = SC_LD(3, sn + 1), n2n = SC_LD(4, sn + 1);
;                 const float v1n = buf[SC_VOFF + sn * 16 + rl], v2n = buf[SC_VOFF + (sn + 1) * 16 + rl];
;                 const f32x2 cfn = *(const f32x2*)(buf + SC_COFF + (pr + 1) * 2);
;                 __builtin_amdgcn_sched_barrier(0x7);
;                 float d1 = dot4(S, q1), e2 = dot4(S, g2);
;                 const f32x4 t1 = S * w1 + v1 * k1;
;                 reduce16x2(d1, e2);
;                 const float d2 = e2 + v1 * cf[0] - d1 * cf[1];
;                 const f32x4 S1 = t1 + d1 * n1;
;                 const f32x4 S2 = (S1 * w2 + v2 * k2) + d2 * n2;
;                 float y1 = dot4(S1, r1), y2 = dot4(S2, r2);
;                 y1 += dppf<0xB1>(y1); y2 += dppf<0xB1>(y2);
;                 float yz = odd_lane ? y2 : y1;
;                 yz += dppf<0x122>(yz); yz += dppf<0x124>(yz); yz += dppf<0x128>(yz);
;                 yb[(2 * pr) * 16 + yoff] = yz;
;                 S = S2;
;                 r1 = r1n; w1 = w1n; k1 = k1n; q1 = q1n; n1 = n1n; r2 = r2n; w2 = w2n; k2 = k2n; g2 = g2n; n2 = n2n; v1 = v1n; v2 = v2n; cf = cfn;
	v_pk_fma_f32 v[0:1], v[82:83], v[108:109], v[110:111] op_sel_hi:[1,0,1]
	v_pk_fma_f32 v[2:3], v[84:85], v[108:109], v[112:113] op_sel_hi:[1,0,1]
	v_add_f32_dpp v124, v124, v124 row_ror:4 row_mask:0xf bank_mask:0xf bound_ctrl:1
	s_nop 0
	s_nop 0
	v_add_f32_dpp v124, v124, v124 row_ror:8 row_mask:0xf bank_mask:0xf bound_ctrl:1
	ds_write_b32 v6, v124 offset:0
	ds_read_b128 v[10:13], v8 offset:26112
	ds_read_b128 v[14:17], v8 offset:26368
	ds_read_b128 v[18:21], v8 offset:17920
	ds_read2_b32 v[50:51], v129 offset0:96 offset1:112
	ds_read_b128 v[22:25], v8 offset:9728
	ds_read_b64 v[52:53], v7 offset:43032
	ds_read_b128 v[26:29], v8 offset:18176
	ds_read_b128 v[30:33], v8 offset:34304
	ds_read_b128 v[34:37], v8 offset:9984
	ds_read_b128 v[38:41], v8 offset:34560
	ds_read_b128 v[42:45], v8 offset:1536
	ds_read_b128 v[46:49], v8 offset:1792
	s_waitcnt lgkmcnt(15)
	v_pk_mul_f32 v[118:119], v[116:117], v[88:89]
	v_pk_mul_f32 v[120:121], v[2:3], v[92:93]
	v_pk_fma_f32 v[118:119], v[114:115], v[86:87], v[118:119]
	v_pk_fma_f32 v[120:121], v[0:1], v[90:91], v[120:121]
	v_add_f32_e32 v122, v118, v119
	v_add_f32_e32 v123, v120, v121
	v_pk_mul_f32 v[98:99], v[2:3], v[180:181]
	v_pk_mul_f32 v[100:101], v[2:3], v[184:185]
	v_pk_fma_f32 v[98:99], v[0:1], v[178:179], v[98:99]
	v_pk_fma_f32 v[100:101], v[0:1], v[182:183], v[100:101]
	v_add_f32_e32 v106, v98, v99
	v_add_f32_e32 v107, v100, v101
	v_pk_mul_f32 v[102:103], v[186:187], v[218:219] op_sel_hi:[1,0]
	v_pk_mul_f32 v[104:105], v[188:189], v[218:219] op_sel_hi:[1,0]
	v_add_f32_dpp v106, v106, v106 quad_perm:[1,0,3,2] row_mask:0xf bank_mask:0xf bound_ctrl:1
	v_add_f32_dpp v107, v107, v107 quad_perm:[1,0,3,2] row_mask:0xf bank_mask:0xf bound_ctrl:1
	v_pk_fma_f32 v[102:103], v[0:1], v[190:191], v[102:103]
	v_pk_fma_f32 v[104:105], v[2:3], v[192:193], v[104:105]
	v_cndmask_b32_e32 v109, v107, v106, vcc
	v_mul_f32_e32 v108, v218, v220
	v_pk_mul_f32 v[110:111], v[194:195], v[218:219] op_sel:[0,1]
	v_add_f32_dpp v109, v109, v109 row_ror:2 row_mask:0xf bank_mask:0xf bound_ctrl:1
	v_pk_mul_f32 v[112:113], v[196:197], v[218:219] op_sel:[0,1]
	v_add_f32_dpp v122, v122, v122 quad_perm:[1,0,3,2] row_mask:0xf bank_mask:0xf bound_ctrl:1
	v_add_f32_dpp v109, v109, v109 row_ror:4 row_mask:0xf bank_mask:0xf bound_ctrl:1
	v_add_f32_dpp v123, v123, v123 quad_perm:[1,0,3,2] row_mask:0xf bank_mask:0xf bound_ctrl:1
	v_cndmask_b32_e32 v124, v123, v122, vcc
	v_add_f32_dpp v109, v109, v109 row_ror:8 row_mask:0xf bank_mask:0xf bound_ctrl:1
	s_nop 0
	v_add_f32_dpp v124, v124, v124 row_ror:2 row_mask:0xf bank_mask:0xf bound_ctrl:1
	v_fmac_f32_dpp v102, v109, v198 quad_perm:[0,0,2,2] row_mask:0xf bank_mask:0xf bound_ctrl:1
	v_fmac_f32_dpp v103, v109, v199 quad_perm:[0,0,2,2] row_mask:0xf bank_mask:0xf bound_ctrl:1
	v_fmac_f32_dpp v104, v109, v200 quad_perm:[0,0,2,2] row_mask:0xf bank_mask:0xf bound_ctrl:1
	v_fmac_f32_dpp v105, v109, v201 quad_perm:[0,0,2,2] row_mask:0xf bank_mask:0xf bound_ctrl:1
	v_fmac_f32_dpp v108, v109, -v221 quad_perm:[0,0,2,2] row_mask:0xf bank_mask:0xf bound_ctrl:1
	v_pk_fma_f32 v[110:111], v[102:103], v[202:203], v[110:111]
	v_pk_fma_f32 v[112:113], v[104:105], v[204:205], v[112:113]
	v_add_f32_dpp v108, v109, v108 quad_perm:[1,1,3,3] row_mask:0xf bank_mask:0xf bound_ctrl:1
	v_pk_fma_f32 v[0:1], v[206:207], v[108:109], v[110:111] op_sel_hi:[1,0,1]
	v_pk_fma_f32 v[2:3], v[208:209], v[108:109], v[112:113] op_sel_hi:[1,0,1]
	v_add_f32_dpp v124, v124, v124 row_ror:4 row_mask:0xf bank_mask:0xf bound_ctrl:1
	s_nop 0
	s_nop 0
	v_add_f32_dpp v124, v124, v124 row_ror:8 row_mask:0xf bank_mask:0xf bound_ctrl:1
	ds_write_b32 v6, v124 offset:128
	ds_read_b128 v[54:57], v8 offset:26624
	ds_read_b128 v[58:61], v8 offset:26880
	ds_read_b128 v[62:65], v8 offset:18432
	ds_read2_b32 v[94:95], v129 offset0:128 offset1:144
	ds_read_b128 v[66:69], v8 offset:10240
	ds_read_b64 v[96:97], v7 offset:43040
	ds_read_b128 v[70:73], v8 offset:18688
	ds_read_b128 v[74:77], v8 offset:34816
	ds_read_b128 v[78:81], v8 offset:10496
	ds_read_b128 v[82:85], v8 offset:35072
	ds_read_b128 v[86:89], v8 offset:2048
	ds_read_b128 v[90:93], v8 offset:2304
	s_waitcnt lgkmcnt(15)
	v_pk_mul_f32 v[118:119], v[104:105], v[212:213]
	v_pk_mul_f32 v[120:121], v[2:3], v[216:217]
	v_pk_fma_f32 v[118:119], v[102:103], v[210:211], v[118:119]
	v_pk_fma_f32 v[120:121], v[0:1], v[214:215], v[120:121]
	v_add_f32_e32 v122, v118, v119
	v_add_f32_e32 v123, v120, v121
	v_pk_mul_f32 v[98:99], v[2:3], v[12:13]
	v_pk_mul_f32 v[100:101], v[2:3], v[16:17]
	v_pk_fma_f32 v[98:99], v[0:1], v[10:11], v[98:99]
	v_pk_fma_f32 v[100:101], v[0:1], v[14:15], v[100:101]
	v_add_f32_e32 v106, v98, v99
	v_add_f32_e32 v107, v100, v101
	v_pk_mul_f32 v[114:115], v[18:19], v[50:51] op_sel_hi:[1,0]
	v_pk_mul_f32 v[116:117], v[20:21], v[50:51] op_sel_hi:[1,0]
	v_add_f32_dpp v106, v106, v106 quad_perm:[1,0,3,2] row_mask:0xf bank_mask:0xf bound_ctrl:1
	v_add_f32_dpp v107, v107, v107 quad_perm:[1,0,3,2] row_mask:0xf bank_mask:0xf bound_ctrl:1
	v_pk_fma_f32 v[114:115], v[0:1], v[22:23], v[114:115]
	v_pk_fma_f32 v[116:117], v[2:3], v[24:25], v[116:117]
	v_cndmask_b32_e32 v109, v107, v106, vcc
	v_mul_f32_e32 v108, v50, v52
	v_pk_mul_f32 v[110:111], v[26:27], v[50:51] op_sel:[0,1]
	v_add_f32_dpp v109, v109, v109 row_ror:2 row_mask:0xf bank_mask:0xf bound_ctrl:1
	v_pk_mul_f32 v[112:113], v[28:29], v[50:51] op_sel:[0,1]
	v_add_f32_dpp v122, v122, v122 quad_perm:[1,0,3,2] row_mask:0xf bank_mask:0xf bound_ctrl:1
	v_add_f32_dpp v109, v109, v109 row_ror:4 row_mask:0xf bank_mask:0xf bound_ctrl:1
	v_add_f32_dpp v123, v123, v123 quad_perm:[1,0,3,2] row_mask:0xf bank_mask:0xf bound_ctrl:1
; template <int CTRL> __device__ __forceinline__ float dppf(float x) { return __builtin_bit_cast(float, __builtin_amdgcn_mov_dpp(__builtin_bit_cast(int, x), CTRL, 0xf, 0xf, true)); }
; __device__ __forceinline__ float dot4(const f32x4& a, const f32x4& b) {
;     f32x2 t = __builtin_shufflevector(a, a, 0, 1) * __builtin_shufflevector(b, b, 0, 1);
;     t = __builtin_shufflevector(a, a, 2, 3) * __builtin_shufflevector(b, b, 2, 3) + t;
;     return t[0] + t[1];
; }
; __device__ __forceinline__ void reduce16x2(float& a, float& b) {
;     a += dppf<0xB1>(a); b += dppf<0xB1>(b); a += dppf<0x4E>(a); b += dppf<0x4E>(b);
;     a += dppf<0x141>(a); b += dppf<0x141>(b); a += dppf<0x140>(a); b += dppf<0x140>(b);
; }
; __device__ __forceinline__ void scan_unit(const Params& p, int unit) {
;     ...
;             for (int pr = 0; pr < SC_TC / 2; ++pr) {
;                 const int sn = 2 * pr + 2;
;                 const f32x4 r1n = SC_LD(0, sn), w1n = SC_LD(1, sn), k1n = SC_LD(2, sn), q1n = SC_LD(3, sn), n1n = SC_LD(4, sn);
;                 const f32x4 r2n = SC_LD(0, sn + 1), w2n = SC_LD(1, sn + 1), k2n = SC_LD(2, sn + 1), g2n = SC_LD(3, sn + 1), n2n = SC_LD(4, sn + 1);
;                 const float v1n = buf[SC_VOFF + sn * 16 + rl], v2n = buf[SC_VOFF + (sn + 1) * 16 + rl];
;                 const f32x2 cfn = *(const f32x2*)(buf + SC_COFF + (pr + 1) * 2);
;                 __builtin_amdgcn_sched_barrier(0x7);
;                 float d1 = dot4(S, q1), e2 = dot4(S, g2);
;                 const f32x4 t1 = S * w1 + v1 * k1;
;                 reduce16x2(d1, e2);
;                 const float d2 = e2 + v1 * cf[0] - d1 * cf[1];
;                 const f32x4 S1 = t1 + d1 * n1;
;                 const f32x4 S2 = (S1 * w2 + v2 * k2) + d2 * n2;
;                 float y1 = dot4(S1, r1), y2 = dot4(S2, r2);
;                 y1 += dppf<0xB1>(y1); y2 += dppf<0xB1>(y2);
;                 float yz = odd_lane ? y2 : y1;
;                 yz += dppf<0x122>(yz); yz += dppf<0x124>(yz); yz += dppf<0x128>(yz);
;                 yb[(2 * pr) * 16 + yoff] = yz;
;                 S = S2;
;                 r1 = r1n; w1 = w1n; k1 = k1n; q1 = q1n; n1 = n1n; r2 = r2n; w2 = w2n; k2 = k2n; g2 = g2n; n2 = n2n; v1 = v1n; v2 = v2n; cf = cfn;
	v_cndmask_b32_e32 v124, v123, v122, vcc
	v_add_f32_dpp v109, v109, v109 row_ror:8 row_mask:0xf bank_mask:0xf bound_ctrl:1
	s_nop 0
	v_add_f32_dpp v124, v124, v124 row_ror:2 row_mask:0xf bank_mask:0xf bound_ctrl:1
	v_fmac_f32_dpp v114, v109, v30 quad_perm:[0,0,2,2] row_mask:0xf bank_mask:0xf bound_ctrl:1
	v_fmac_f32_dpp v115, v109, v31 quad_perm:[0,0,2,2] row_mask:0xf bank_mask:0xf bound_ctrl:1
	v_fmac_f32_dpp v116, v109, v32 quad_perm:[0,0,2,2] row_mask:0xf bank_mask:0xf bound_ctrl:1
	v_fmac_f32_dpp v117, v109, v33 quad_perm:[0,0,2,2] row_mask:0xf bank_mask:0xf bound_ctrl:1
	v_fmac_f32_dpp v108, v109, -v53 quad_perm:[0,0,2,2] row_mask:0xf bank_mask:0xf bound_ctrl:1
	v_pk_fma_f32 v[110:111], v[114:115], v[34:35], v[110:111]
	v_pk_fma_f32 v[112:113], v[116:117], v[36:37], v[112:113]
	v_add_f32_dpp v108, v109, v108 quad_perm:[1,1,3,3] row_mask:0xf bank_mask:0xf bound_ctrl:1
	v_pk_fma_f32 v[0:1], v[38:39], v[108:109], v[110:111] op_sel_hi:[1,0,1]
	v_pk_fma_f32 v[2:3], v[40:41], v[108:109], v[112:113] op_sel_hi:[1,0,1]
	v_add_f32_dpp v124, v124, v124 row_ror:4 row_mask:0xf bank_mask:0xf bound_ctrl:1
	s_nop 0
	s_nop 0
	v_add_f32_dpp v124, v124, v124 row_ror:8 row_mask:0xf bank_mask:0xf bound_ctrl:1
	ds_write_b32 v6, v124 offset:256
	ds_read_b128 v[178:181], v8 offset:27136
	ds_read_b128 v[182:185], v8 offset:27392
	ds_read_b128 v[186:189], v8 offset:18944
	ds_read2_b32 v[218:219], v129 offset0:160 offset1:176
	ds_read_b128 v[190:193], v8 offset:10752
	ds_read_b64 v[220:221], v7 offset:43048
	ds_read_b128 v[194:197], v8 offset:19200
	ds_read_b128 v[198:201], v8 offset:35328
	ds_read_b128 v[202:205], v8 offset:11008
	ds_read_b128 v[206:209], v8 offset:35584
	ds_read_b128 v[210:213], v8 offset:2560
	ds_read_b128 v[214:217], v8 offset:2816
	s_waitcnt lgkmcnt(15)
	v_pk_mul_f32 v[118:119], v[116:117], v[44:45]
	v_pk_mul_f32 v[120:121], v[2:3], v[48:49]
	v_pk_fma_f32 v[118:119], v[114:115], v[42:43], v[118:119]
	v_pk_fma_f32 v[120:121], v[0:1], v[46:47], v[120:121]
	v_add_f32_e32 v122, v118, v119
	v_add_f32_e32 v123, v120, v121
	v_pk_mul_f32 v[98:99], v[2:3], v[56:57]
	v_pk_mul_f32 v[100:101], v[2:3], v[60:61]
	v_pk_fma_f32 v[98:99], v[0:1], v[54:55], v[98:99]
	v_pk_fma_f32 v[100:101], v[0:1], v[58:59], v[100:101]
	v_add_f32_e32 v106, v98, v99
	v_add_f32_e32 v107, v100, v101
	v_pk_mul_f32 v[102:103], v[62:63], v[94:95] op_sel_hi:[1,0]
	v_pk_mul_f32 v[104:105], v[64:65], v[94:95] op_sel_hi:[1,0]
	v_add_f32_dpp v106, v106, v106 quad_perm:[1,0,3,2] row_mask:0xf bank_mask:0xf bound_ctrl:1
	v_add_f32_dpp v107, v107, v107 quad_perm:[1,0,3,2] row_mask:0xf bank_mask:0xf bound_ctrl:1
	v_pk_fma_f32 v[102:103], v[0:1], v[66:67], v[102:103]
	v_pk_fma_f32 v[104:105], v[2:3], v[68:69], v[104:105]
	v_cndmask_b32_e32 v109, v107, v106, vcc
	v_mul_f32_e32 v108, v94, v96
	v_pk_mul_f32 v[110:111], v[70:71], v[94:95] op_sel:[0,1]
	v_add_f32_dpp v109, v109, v109 row_ror:2 row_mask:0xf bank_mask:0xf bound_ctrl:1
	v_pk_mul_f32 v[112:113], v[72:73], v[94:95] op_sel:[0,1]
	v_add_f32_dpp v122, v122, v122 quad_perm:[1,0,3,2] row_mask:0xf bank_mask:0xf bound_ctrl:1
	v_add_f32_dpp v109, v109, v109 row_ror:4 row_mask:0xf bank_mask:0xf bound_ctrl:1
	v_add_f32_dpp v123, v123, v123 quad_perm:[1,0,3,2] row_mask:0xf bank_mask:0xf bound_ctrl:1
	v_cndmask_b32_e32 v124, v123, v122, vcc
	v_add_f32_dpp v109, v109, v109 row_ror:8 row_mask:0xf bank_mask:0xf bound_ctrl:1
	s_nop 0
	v_add_f32_dpp v124, v124, v124 row_ror:2 row_mask:0xf bank_mask:0xf bound_ctrl:1
	v_fmac_f32_dpp v102, v109, v74 quad_perm:[0,0,2,2] row_mask:0xf bank_mask:0xf bound_ctrl:1
	v_fmac_f32_dpp v103, v109, v75 quad_perm:[0,0,2,2] row_mask:0xf bank_mask:0xf bound_ctrl:1
	v_fmac_f32_dpp v104, v109, v76 quad_perm:[0,0,2,2] row_mask:0xf bank_mask:0xf bound_ctrl:1
	v_fmac_f32_dpp v105, v109, v77 quad_perm:[0,0,2,2] row_mask:0xf bank_mask:0xf bound_ctrl:1
	v_fmac_f32_dpp v108, v109, -v97 quad_perm:[0,0,2,2] row_mask:0xf bank_mask:0xf bound_ctrl:1
	v_pk_fma_f32 v[110:111], v[102:103], v[78:79], v[110:111]
	v_pk_fma_f32 v[112:113], v[104:105], v[80:81], v[112:113]
	v_add_f32_dpp v108, v109, v108 quad_perm:[1,1,3,3] row_mask:0xf bank_mask:0xf bound_ctrl:1
	v_pk_fma_f32 v[0:1], v[82:83], v[108:109], v[110:111] op_sel_hi:[1,0,1]
	v_pk_fma_f32 v[2:3], v[84:85], v[108:109], v[112:113] op_sel_hi:[1,0,1]
	v_add_f32_dpp v124, v124, v124 row_ror:4 row_mask:0xf bank_mask:0xf bound_ctrl:1
	s_nop 0
	s_nop 0
	v_add_f32_dpp v124, v124, v124 row_ror:8 row_mask:0xf bank_mask:0xf bound_ctrl:1
	ds_write_b32 v6, v124 offset:384
	ds_read_b128 v[10:13], v8 offset:27648
	ds_read_b128 v[14:17], v8 offset:27904
	ds_read_b128 v[18:21], v8 offset:19456
	ds_read2_b32 v[50:51], v129 offset0:192 offset1:208
	ds_read_b128 v[22:25], v8 offset:11264
	ds_read_b64 v[52:53], v7 offset:43056
	ds_read_b128 v[26:29], v8 offset:19712
	ds_read_b128 v[30:33], v8 offset:35840
	ds_read_b128 v[34:37], v8 offset:11520
	ds_read_b128 v[38:41], v8 offset:36096
	ds_read_b128 v[42:45], v8 offset:3072
	ds_read_b128 v[46:49], v8 offset:3328
	s_waitcnt lgkmcnt(15)
; template <int CTRL> __device__ __forceinline__ float dppf(float x) { return __builtin_bit_cast(float, __builtin_amdgcn_mov_dpp(__builtin_bit_cast(int, x), CTRL, 0xf, 0xf, true)); }
; __device__ __forceinline__ float dot4(const f32x4& a, const f32x4& b) {
;     f32x2 t = __builtin_shufflevector(a, a, 0, 1) * __builtin_shufflevector(b, b, 0, 1);
;     t = __builtin_shufflevector(a, a, 2, 3) * __builtin_shufflevector(b, b, 2, 3) + t;
;     return t[0] + t[1];
; }
; __device__ __forceinline__ void reduce16x2(float& a, float& b) {
;     a += dppf<0xB1>(a); b += dppf<0xB1>(b); a += dppf<0x4E>(a); b += dppf<0x4E>(b);
;     a += dppf<0x141>(a); b += dppf<0x141>(b); a += dppf<0x140>(a); b += dppf<0x140>(b);
; }
; __device__ __forceinline__ void scan_unit(const Params& p, int unit) {
;     ...
;             for (int pr = 0; pr < SC_TC / 2; ++pr) {
;                 const int sn = 2 * pr + 2;
;                 const f32x4 r1n = SC_LD(0, sn), w1n = SC_LD(1, sn), k1n = SC_LD(2, sn), q1n = SC_LD(3, sn), n1n = SC_LD(4, sn);
;                 const f32x4 r2n = SC_LD(0, sn + 1), w2n = SC_LD(1, sn + 1), k2n = SC_LD(2, sn + 1), g2n = SC_LD(3, sn + 1), n2n = SC_LD(4, sn + 1);
;                 const float v1n = buf[SC_VOFF + sn * 16 + rl], v2n = buf[SC_VOFF + (sn + 1) * 16 + rl];
;                 const f32x2 cfn = *(const f32x2*)(buf + SC_COFF + (pr + 1) * 2);
;                 __builtin_amdgcn_sched_barrier(0x7);
;                 float d1 = dot4(S, q1), e2 = dot4(S, g2);
;                 const f32x4 t1 = S * w1 + v1 * k1;
;                 reduce16x2(d1, e2);
;                 const float d2 = e2 + v1 * cf[0] - d1 * cf[1];
;                 const f32x4 S1 = t1 + d1 * n1;
;                 const f32x4 S2 = (S1 * w2 + v2 * k2) + d2 * n2;
;                 float y1 = dot4(S1, r1), y2 = dot4(S2, r2);
;                 y1 += dppf<0xB1>(y1); y2 += dppf<0xB1>(y2);
;                 float yz = odd_lane ? y2 : y1;
;                 yz += dppf<0x122>(yz); yz += dppf<0x124>(yz); yz += dppf<0x128>(yz);
;                 yb[(2 * pr) * 16 + yoff] = yz;
;                 S = S2;
;                 r1 = r1n; w1 = w1n; k1 = k1n; q1 = q1n; n1 = n1n; r2 = r2n; w2 = w2n; k2 = k2n; g2 = g2n; n2 = n2n; v1 = v1n; v2 = v2n; cf = cfn;
	v_pk_mul_f32 v[118:119], v[104:105], v[88:89]
	v_pk_mul_f32 v[120:121], v[2:3], v[92:93]
	v_pk_fma_f32 v[118:119], v[102:103], v[86:87], v[118:119]
	v_pk_fma_f32 v[120:121], v[0:1], v[90:91], v[120:121]
	v_add_f32_e32 v122, v118, v119
	v_add_f32_e32 v123, v120, v121
	v_pk_mul_f32 v[98:99], v[2:3], v[180:181]
	v_pk_mul_f32 v[100:101], v[2:3], v[184:185]
	v_pk_fma_f32 v[98:99], v[0:1], v[178:179], v[98:99]
	v_pk_fma_f32 v[100:101], v[0:1], v[182:183], v[100:101]
	v_add_f32_e32 v106, v98, v99
	v_add_f32_e32 v107, v100, v101
	v_pk_mul_f32 v[114:115], v[186:187], v[218:219] op_sel_hi:[1,0]
	v_pk_mul_f32 v[116:117], v[188:189], v[218:219] op_sel_hi:[1,0]
	v_add_f32_dpp v106, v106, v106 quad_perm:[1,0,3,2] row_mask:0xf bank_mask:0xf bound_ctrl:1
	v_add_f32_dpp v107, v107, v107 quad_perm:[1,0,3,2] row_mask:0xf bank_mask:0xf bound_ctrl:1
	v_pk_fma_f32 v[114:115], v[0:1], v[190:191], v[114:115]
	v_pk_fma_f32 v[116:117], v[2:3], v[192:193], v[116:117]
	v_cndmask_b32_e32 v109, v107, v106, vcc
	v_mul_f32_e32 v108, v218, v220
	v_pk_mul_f32 v[110:111], v[194:195], v[218:219] op_sel:[0,1]
	v_add_f32_dpp v109, v109, v109 row_ror:2 row_mask:0xf bank_mask:0xf bound_ctrl:1
	v_pk_mul_f32 v[112:113], v[196:197], v[218:219] op_sel:[0,1]
	v_add_f32_dpp v122, v122, v122 quad_perm:[1,0,3,2] row_mask:0xf bank_mask:0xf bound_ctrl:1
	v_add_f32_dpp v109, v109, v109 row_ror:4 row_mask:0xf bank_mask:0xf bound_ctrl:1
	v_add_f32_dpp v123, v123, v123 quad_perm:[1,0,3,2] row_mask:0xf bank_mask:0xf bound_ctrl:1
	v_cndmask_b32_e32 v124, v123, v122, vcc
	v_add_f32_dpp v109, v109, v109 row_ror:8 row_mask:0xf bank_mask:0xf bound_ctrl:1
	s_nop 0
	v_add_f32_dpp v124, v124, v124 row_ror:2 row_mask:0xf bank_mask:0xf bound_ctrl:1
	v_fmac_f32_dpp v114, v109, v198 quad_perm:[0,0,2,2] row_mask:0xf bank_mask:0xf bound_ctrl:1
	v_fmac_f32_dpp v115, v109, v199 quad_perm:[0,0,2,2] row_mask:0xf bank_mask:0xf bound_ctrl:1
	v_fmac_f32_dpp v116, v109, v200 quad_perm:[0,0,2,2] row_mask:0xf bank_mask:0xf bound_ctrl:1
	v_fmac_f32_dpp v117, v109, v201 quad_perm:[0,0,2,2] row_mask:0xf bank_mask:0xf bound_ctrl:1
	v_fmac_f32_dpp v108, v109, -v221 quad_perm:[0,0,2,2] row_mask:0xf bank_mask:0xf bound_ctrl:1
	v_pk_fma_f32 v[110:111], v[114:115], v[202:203], v[110:111]
	v_pk_fma_f32 v[112:113], v[116:117], v[204:205], v[112:113]
	v_add_f32_dpp v108, v109, v108 quad_perm:[1,1,3,3] row_mask:0xf bank_mask:0xf bound_ctrl:1
	v_pk_fma_f32 v[0:1], v[206:207], v[108:109], v[110:111] op_sel_hi:[1,0,1]
	v_pk_fma_f32 v[2:3], v[208:209], v[108:109], v[112:113] op_sel_hi:[1,0,1]
	v_add_f32_dpp v124, v124, v124 row_ror:4 row_mask:0xf bank_mask:0xf bound_ctrl:1
	s_nop 0
	s_nop 0
	v_add_f32_dpp v124, v124, v124 row_ror:8 row_mask:0xf bank_mask:0xf bound_ctrl:1
	ds_write_b32 v6, v124 offset:512
	ds_read_b128 v[54:57], v8 offset:28160
	ds_read_b128 v[58:61], v8 offset:28416
	ds_read_b128 v[62:65], v8 offset:19968
	ds_read2_b32 v[94:95], v129 offset0:224 offset1:240
	ds_read_b128 v[66:69], v8 offset:11776
	ds_read_b64 v[96:97], v7 offset:43064
	ds_read_b128 v[70:73], v8 offset:20224
	ds_read_b128 v[74:77], v8 offset:36352
	ds_read_b128 v[78:81], v8 offset:12032
	ds_read_b128 v[82:85], v8 offset:36608
	ds_read_b128 v[86:89], v8 offset:3584
	ds_read_b128 v[90:93], v8 offset:3840
	s_waitcnt lgkmcnt(15)
	v_pk_mul_f32 v[118:119], v[116:117], v[212:213]
	v_pk_mul_f32 v[120:121], v[2:3], v[216:217]
	v_pk_fma_f32 v[118:119], v[114:115], v[210:211], v[118:119]
	v_pk_fma_f32 v[120:121], v[0:1], v[214:215], v[120:121]
	v_add_f32_e32 v122, v118, v119
	v_add_f32_e32 v123, v120, v121
	v_pk_mul_f32 v[98:99], v[2:3], v[12:13]
	v_pk_mul_f32 v[100:101], v[2:3], v[16:17]
	v_pk_fma_f32 v[98:99], v[0:1], v[10:11], v[98:99]
	v_pk_fma_f32 v[100:101], v[0:1], v[14:15], v[100:101]
	v_add_f32_e32 v106, v98, v99
	v_add_f32_e32 v107, v100, v101
	v_pk_mul_f32 v[102:103], v[18:19], v[50:51] op_sel_hi:[1,0]
	v_pk_mul_f32 v[104:105], v[20:21], v[50:51] op_sel_hi:[1,0]
	v_add_f32_dpp v106, v106, v106 quad_perm:[1,0,3,2] row_mask:0xf bank_mask:0xf bound_ctrl:1
	v_add_f32_dpp v107, v107, v107 quad_perm:[1,0,3,2] row_mask:0xf bank_mask:0xf bound_ctrl:1
	v_pk_fma_f32 v[102:103], v[0:1], v[22:23], v[102:103]
	v_pk_fma_f32 v[104:105], v[2:3], v[24:25], v[104:105]
	v_cndmask_b32_e32 v109, v107, v106, vcc
	v_mul_f32_e32 v108, v50, v52
	v_pk_mul_f32 v[110:111], v[26:27], v[50:51] op_sel:[0,1]
	v_add_f32_dpp v109, v109, v109 row_ror:2 row_mask:0xf bank_mask:0xf bound_ctrl:1
	v_pk_mul_f32 v[112:113], v[28:29], v[50:51] op_sel:[0,1]
	v_add_f32_dpp v122, v122, v122 quad_perm:[1,0,3,2] row_mask:0xf bank_mask:0xf bound_ctrl:1
	v_add_f32_dpp v109, v109, v109 row_ror:4 row_mask:0xf bank_mask:0xf bound_ctrl:1
	v_add_f32_dpp v123, v123, v123 quad_perm:[1,0,3,2] row_mask:0xf bank_mask:0xf bound_ctrl:1
	v_cndmask_b32_e32 v124, v123, v122, vcc
	v_add_f32_dpp v109, v109, v109 row_ror:8 row_mask:0xf bank_mask:0xf bound_ctrl:1
	s_nop 0
	v_add_f32_dpp v124, v124, v124 row_ror:2 row_mask:0xf bank_mask:0xf bound_ctrl:1
	v_fmac_f32_dpp v102, v109, v30 quad_perm:[0,0,2,2] row_mask:0xf bank_mask:0xf bound_ctrl:1
	v_fmac_f32_dpp v103, v109, v31 quad_perm:[0,0,2,2] row_mask:0xf bank_mask:0xf bound_ctrl:1
	v_fmac_f32_dpp v104, v109, v32 quad_perm:[0,0,2,2] row_mask:0xf bank_mask:0xf bound_ctrl:1
	v_fmac_f32_dpp v105, v109, v33 quad_perm:[0,0,2,2] row_mask:0xf bank_mask:0xf bound_ctrl:1
	v_fmac_f32_dpp v108, v109, -v53 quad_perm:[0,0,2,2] row_mask:0xf bank_mask:0xf bound_ctrl:1
	v_pk_fma_f32 v[110:111], v[102:103], v[34:35], v[110:111]
	v_pk_fma_f32 v[112:113], v[104:105], v[36:37], v[112:113]
	v_add_f32_dpp v108, v109, v108 quad_perm:[1,1,3,3] row_mask:0xf bank_mask:0xf bound_ctrl:1
	v_pk_fma_f32 v[0:1], v[38:39], v[108:109], v[110:111] op_sel_hi:[1,0,1]
	v_pk_fma_f32 v[2:3], v[40:41], v[108:109], v[112:113] op_sel_hi:[1,0,1]
	v_add_f32_dpp v124, v124, v124 row_ror:4 row_mask:0xf bank_mask:0xf bound_ctrl:1
	s_nop 0
	s_nop 0
	v_add_f32_dpp v124, v124, v124 row_ror:8 row_mask:0xf bank_mask:0xf bound_ctrl:1
	ds_write_b32 v6, v124 offset:640
	ds_read_b128 v[178:181], v8 offset:28672
	ds_read_b128 v[182:185], v8 offset:28928
	ds_read_b128 v[186:189], v8 offset:20480
	ds_read2_b32 v[218:219], v126 offset0:0 offset1:16
	ds_read_b128 v[190:193], v8 offset:12288
	ds_read_b64 v[220:221], v7 offset:43072
	ds_read_b128 v[194:197], v8 offset:20736
	ds_read_b128 v[198:201], v8 offset:36864
	ds_read_b128 v[202:205], v8 offset:12544
	ds_read_b128 v[206:209], v8 offset:37120
	ds_read_b128 v[210:213], v8 offset:4096
	ds_read_b128 v[214:217], v8 offset:4352
	s_waitcnt lgkmcnt(15)
; template <int CTRL> __device__ __forceinline__ float dppf(float x) { return __builtin_bit_cast(float, __builtin_amdgcn_mov_dpp(__builtin_bit_cast(int, x), CTRL, 0xf, 0xf, true)); }
; __device__ __forceinline__ float dot4(const f32x4& a, const f32x4& b) {
;     f32x2 t = __builtin_shufflevector(a, a, 0, 1) * __builtin_shufflevector(b, b, 0, 1);
;     t = __builtin_shufflevector(a, a, 2, 3) * __builtin_shufflevector(b, b, 2, 3) + t;
;     return t[0] + t[1];
; }
; __device__ __forceinline__ void reduce16x2(float& a, float& b) {
;     a += dppf<0xB1>(a); b += dppf<0xB1>(b); a += dppf<0x4E>(a); b += dppf<0x4E>(b);
;     a += dppf<0x141>(a); b += dppf<0x141>(b); a += dppf<0x140>(a); b += dppf<0x140>(b);
; }
; __device__ __forceinline__ void scan_unit(const Params& p, int unit) {
;     ...
;             for (int pr = 0; pr < SC_TC / 2; ++pr) {
;                 const int sn = 2 * pr + 2;
;                 const f32x4 r1n = SC_LD(0, sn), w1n = SC_LD(1, sn), k1n = SC_LD(2, sn), q1n = SC_LD(3, sn), n1n = SC_LD(4, sn);
;                 const f32x4 r2n = SC_LD(0, sn + 1), w2n = SC_LD(1, sn + 1), k2n = SC_LD(2, sn + 1), g2n = SC_LD(3, sn + 1), n2n = SC_LD(4, sn + 1);
;                 const float v1n = buf[SC_VOFF + sn * 16 + rl], v2n = buf[SC_VOFF + (sn + 1) * 16 + rl];
;                 const f32x2 cfn = *(const f32x2*)(buf + SC_COFF + (pr + 1) * 2);
;                 __builtin_amdgcn_sched_barrier(0x7);
;                 float d1 = dot4(S, q1), e2 = dot4(S, g2);
;                 const f32x4 t1 = S * w1 + v1 * k1;
;                 reduce16x2(d1, e2);
;                 const float d2 = e2 + v1 * cf[0] - d1 * cf[1];
;                 const f32x4 S1 = t1 + d1 * n1;
;                 const f32x4 S2 = (S1 * w2 + v2 * k2) + d2 * n2;
;                 float y1 = dot4(S1, r1), y2 = dot4(S2, r2);
;                 y1 += dppf<0xB1>(y1); y2 += dppf<0xB1>(y2);
;                 float yz = odd_lane ? y2 : y1;
;                 yz += dppf<0x122>(yz); yz += dppf<0x124>(yz); yz += dppf<0x128>(yz);
;                 yb[(2 * pr) * 16 + yoff] = yz;
;                 S = S2;
;                 r1 = r1n; w1 = w1n; k1 = k1n; q1 = q1n; n1 = n1n; r2 = r2n; w2 = w2n; k2 = k2n; g2 = g2n; n2 = n2n; v1 = v1n; v2 = v2n; cf = cfn;
	v_pk_mul_f32 v[118:119], v[104:105], v[44:45]
	v_pk_mul_f32 v[120:121], v[2:3], v[48:49]
	v_pk_fma_f32 v[118:119], v[102:103], v[42:43], v[118:119]
	v_pk_fma_f32 v[120:121], v[0:1], v[46:47], v[120:121]
	v_add_f32_e32 v122, v118, v119
	v_add_f32_e32 v123, v120, v121
	v_pk_mul_f32 v[98:99], v[2:3], v[56:57]
	v_pk_mul_f32 v[100:101], v[2:3], v[60:61]
	v_pk_fma_f32 v[98:99], v[0:1], v[54:55], v[98:99]
	v_pk_fma_f32 v[100:101], v[0:1], v[58:59], v[100:101]
	v_add_f32_e32 v106, v98, v99
	v_add_f32_e32 v107, v100, v101
	v_pk_mul_f32 v[114:115], v[62:63], v[94:95] op_sel_hi:[1,0]
	v_pk_mul_f32 v[116:117], v[64:65], v[94:95] op_sel_hi:[1,0]
	v_add_f32_dpp v106, v106, v106 quad_perm:[1,0,3,2] row_mask:0xf bank_mask:0xf bound_ctrl:1
	v_add_f32_dpp v107, v107, v107 quad_perm:[1,0,3,2] row_mask:0xf bank_mask:0xf bound_ctrl:1
	v_pk_fma_f32 v[114:115], v[0:1], v[66:67], v[114:115]
	v_pk_fma_f32 v[116:117], v[2:3], v[68:69], v[116:117]
	v_cndmask_b32_e32 v109, v107, v106, vcc
	v_mul_f32_e32 v108, v94, v96
	v_pk_mul_f32 v[110:111], v[70:71], v[94:95] op_sel:[0,1]
	v_add_f32_dpp v109, v109, v109 row_ror:2 row_mask:0xf bank_mask:0xf bound_ctrl:1
	v_pk_mul_f32 v[112:113], v[72:73], v[94:95] op_sel:[0,1]
	v_add_f32_dpp v122, v122, v122 quad_perm:[1,0,3,2] row_mask:0xf bank_mask:0xf bound_ctrl:1
	v_add_f32_dpp v109, v109, v109 row_ror:4 row_mask:0xf bank_mask:0xf bound_ctrl:1
	v_add_f32_dpp v123, v123, v123 quad_perm:[1,0,3,2] row_mask:0xf bank_mask:0xf bound_ctrl:1
	v_cndmask_b32_e32 v124, v123, v122, vcc
	v_add_f32_dpp v109, v109, v109 row_ror:8 row_mask:0xf bank_mask:0xf bound_ctrl:1
	s_nop 0
	v_add_f32_dpp v124, v124, v124 row_ror:2 row_mask:0xf bank_mask:0xf bound_ctrl:1
	v_fmac_f32_dpp v114, v109, v74 quad_perm:[0,0,2,2] row_mask:0xf bank_mask:0xf bound_ctrl:1
	v_fmac_f32_dpp v115, v109, v75 quad_perm:[0,0,2,2] row_mask:0xf bank_mask:0xf bound_ctrl:1
	v_fmac_f32_dpp v116, v109, v76 quad_perm:[0,0,2,2] row_mask:0xf bank_mask:0xf bound_ctrl:1
	v_fmac_f32_dpp v117, v109, v77 quad_perm:[0,0,2,2] row_mask:0xf bank_mask:0xf bound_ctrl:1
	v_fmac_f32_dpp v108, v109, -v97 quad_perm:[0,0,2,2] row_mask:0xf bank_mask:0xf bound_ctrl:1
	v_pk_fma_f32 v[110:111], v[114:115], v[78:79], v[110:111]
	v_pk_fma_f32 v[112:113], v[116:117], v[80:81], v[112:113]
	v_add_f32_dpp v108, v109, v108 quad_perm:[1,1,3,3] row_mask:0xf bank_mask:0xf bound_ctrl:1
	v_pk_fma_f32 v[0:1], v[82:83], v[108:109], v[110:111] op_sel_hi:[1,0,1]
	v_pk_fma_f32 v[2:3], v[84:85], v[108:109], v[112:113] op_sel_hi:[1,0,1]
	v_add_f32_dpp v124, v124, v124 row_ror:4 row_mask:0xf bank_mask:0xf bound_ctrl:1
	s_nop 0
	s_nop 0
	v_add_f32_dpp v124, v124, v124 row_ror:8 row_mask:0xf bank_mask:0xf bound_ctrl:1
	ds_write_b32 v6, v124 offset:768
	ds_read_b128 v[10:13], v8 offset:29184
	ds_read_b128 v[14:17], v8 offset:29440
	ds_read_b128 v[18:21], v8 offset:20992
	ds_read2_b32 v[50:51], v126 offset0:32 offset1:48
	ds_read_b128 v[22:25], v8 offset:12800
	ds_read_b64 v[52:53], v7 offset:43080
	ds_read_b128 v[26:29], v8 offset:21248
	ds_read_b128 v[30:33], v8 offset:37376
	ds_read_b128 v[34:37], v8 offset:13056
	ds_read_b128 v[38:41], v8 offset:37632
	ds_read_b128 v[42:45], v8 offset:4608
	ds_read_b128 v[46:49], v8 offset:4864
	s_waitcnt lgkmcnt(15)
	v_pk_mul_f32 v[118:119], v[116:117], v[88:89]
	v_pk_mul_f32 v[120:121], v[2:3], v[92:93]
	v_pk_fma_f32 v[118:119], v[114:115], v[86:87], v[118:119]
	v_pk_fma_f32 v[120:121], v[0:1], v[90:91], v[120:121]
	v_add_f32_e32 v122, v118, v119
	v_add_f32_e32 v123, v120, v121
	v_pk_mul_f32 v[98:99], v[2:3], v[180:181]
	v_pk_mul_f32 v[100:101], v[2:3], v[184:185]
	v_pk_fma_f32 v[98:99], v[0:1], v[178:179], v[98:99]
	v_pk_fma_f32 v[100:101], v[0:1], v[182:183], v[100:101]
	v_add_f32_e32 v106, v98, v99
	v_add_f32_e32 v107, v100, v101
	v_pk_mul_f32 v[102:103], v[186:187], v[218:219] op_sel_hi:[1,0]
	v_pk_mul_f32 v[104:105], v[188:189], v[218:219] op_sel_hi:[1,0]
	v_add_f32_dpp v106, v106, v106 quad_perm:[1,0,3,2] row_mask:0xf bank_mask:0xf bound_ctrl:1
	v_add_f32_dpp v107, v107, v107 quad_perm:[1,0,3,2] row_mask:0xf bank_mask:0xf bound_ctrl:1
	v_pk_fma_f32 v[102:103], v[0:1], v[190:191], v[102:103]
	v_pk_fma_f32 v[104:105], v[2:3], v[192:193], v[104:105]
	v_cndmask_b32_e32 v109, v107, v106, vcc
	v_mul_f32_e32 v108, v218, v220
	v_pk_mul_f32 v[110:111], v[194:195], v[218:219] op_sel:[0,1]
	v_add_f32_dpp v109, v109, v109 row_ror:2 row_mask:0xf bank_mask:0xf bound_ctrl:1
	v_pk_mul_f32 v[112:113], v[196:197], v[218:219] op_sel:[0,1]
	v_add_f32_dpp v122, v122, v122 quad_perm:[1,0,3,2] row_mask:0xf bank_mask:0xf bound_ctrl:1
	v_add_f32_dpp v109, v109, v109 row_ror:4 row_mask:0xf bank_mask:0xf bound_ctrl:1
	v_add_f32_dpp v123, v123, v123 quad_perm:[1,0,3,2] row_mask:0xf bank_mask:0xf bound_ctrl:1
	v_cndmask_b32_e32 v124, v123, v122, vcc
	v_add_f32_dpp v109, v109, v109 row_ror:8 row_mask:0xf bank_mask:0xf bound_ctrl:1
	s_nop 0
	v_add_f32_dpp v124, v124, v124 row_ror:2 row_mask:0xf bank_mask:0xf bound_ctrl:1
	v_fmac_f32_dpp v102, v109, v198 quad_perm:[0,0,2,2] row_mask:0xf bank_mask:0xf bound_ctrl:1
	v_fmac_f32_dpp v103, v109, v199 quad_perm:[0,0,2,2] row_mask:0xf bank_mask:0xf bound_ctrl:1
	v_fmac_f32_dpp v104, v109, v200 quad_perm:[0,0,2,2] row_mask:0xf bank_mask:0xf bound_ctrl:1
	v_fmac_f32_dpp v105, v109, v201 quad_perm:[0,0,2,2] row_mask:0xf bank_mask:0xf bound_ctrl:1
	v_fmac_f32_dpp v108, v109, -v221 quad_perm:[0,0,2,2] row_mask:0xf bank_mask:0xf bound_ctrl:1
	v_pk_fma_f32 v[110:111], v[102:103], v[202:203], v[110:111]
	v_pk_fma_f32 v[112:113], v[104:105], v[204:205], v[112:113]
	v_add_f32_dpp v108, v109, v108 quad_perm:[1,1,3,3] row_mask:0xf bank_mask:0xf bound_ctrl:1
	v_pk_fma_f32 v[0:1], v[206:207], v[108:109], v[110:111] op_sel_hi:[1,0,1]
	v_pk_fma_f32 v[2:3], v[208:209], v[108:109], v[112:113] op_sel_hi:[1,0,1]
	v_add_f32_dpp v124, v124, v124 row_ror:4 row_mask:0xf bank_mask:0xf bound_ctrl:1
	s_nop 0
	s_nop 0
	v_add_f32_dpp v124, v124, v124 row_ror:8 row_mask:0xf bank_mask:0xf bound_ctrl:1
	ds_write_b32 v6, v124 offset:896
	ds_read_b128 v[54:57], v8 offset:29696
	ds_read_b128 v[58:61], v8 offset:29952
	ds_read_b128 v[62:65], v8 offset:21504
	ds_read2_b32 v[94:95], v126 offset0:64 offset1:80
	ds_read_b128 v[66:69], v8 offset:13312
	ds_read_b64 v[96:97], v7 offset:43088
	ds_read_b128 v[70:73], v8 offset:21760
	ds_read_b128 v[74:77], v8 offset:37888
	ds_read_b128 v[78:81], v8 offset:13568
	ds_read_b128 v[82:85], v8 offset:38144
	ds_read_b128 v[86:89], v8 offset:5120
	ds_read_b128 v[90:93], v8 offset:5376
	s_waitcnt lgkmcnt(15)
; template <int CTRL> __device__ __forceinline__ float dppf(float x) { return __builtin_bit_cast(float, __builtin_amdgcn_mov_dpp(__builtin_bit_cast(int, x), CTRL, 0xf, 0xf, true)); }
; __device__ __forceinline__ float dot4(const f32x4& a, const f32x4& b) {
;     f32x2 t = __builtin_shufflevector(a, a, 0, 1) * __builtin_shufflevector(b, b, 0, 1);
;     t = __builtin_shufflevector(a, a, 2, 3) * __builtin_shufflevector(b, b, 2, 3) + t;
;     return t[0] + t[1];
; }
; __device__ __forceinline__ void reduce16x2(float& a, float& b) {
;     a += dppf<0xB1>(a); b += dppf<0xB1>(b); a += dppf<0x4E>(a); b += dppf<0x4E>(b);
;     a += dppf<0x141>(a); b += dppf<0x141>(b); a += dppf<0x140>(a); b += dppf<0x140>(b);
; }
; __device__ __forceinline__ void scan_unit(const Params& p, int unit) {
;     ...
;             for (int pr = 0; pr < SC_TC / 2; ++pr) {
;                 const int sn = 2 * pr + 2;
;                 const f32x4 r1n = SC_LD(0, sn), w1n = SC_LD(1, sn), k1n = SC_LD(2, sn), q1n = SC_LD(3, sn), n1n = SC_LD(4, sn);
;                 const f32x4 r2n = SC_LD(0, sn + 1), w2n = SC_LD(1, sn + 1), k2n = SC_LD(2, sn + 1), g2n = SC_LD(3, sn + 1), n2n = SC_LD(4, sn + 1);
;                 const float v1n = buf[SC_VOFF + sn * 16 + rl], v2n = buf[SC_VOFF + (sn + 1) * 16 + rl];
;                 const f32x2 cfn = *(const f32x2*)(buf + SC_COFF + (pr + 1) * 2);
;                 __builtin_amdgcn_sched_barrier(0x7);
;                 float d1 = dot4(S, q1), e2 = dot4(S, g2);
;                 const f32x4 t1 = S * w1 + v1 * k1;
;                 reduce16x2(d1, e2);
;                 const float d2 = e2 + v1 * cf[0] - d1 * cf[1];
;                 const f32x4 S1 = t1 + d1 * n1;
;                 const f32x4 S2 = (S1 * w2 + v2 * k2) + d2 * n2;
;                 float y1 = dot4(S1, r1), y2 = dot4(S2, r2);
;                 y1 += dppf<0xB1>(y1); y2 += dppf<0xB1>(y2);
;                 float yz = odd_lane ? y2 : y1;
;                 yz += dppf<0x122>(yz); yz += dppf<0x124>(yz); yz += dppf<0x128>(yz);
;                 yb[(2 * pr) * 16 + yoff] = yz;
;                 S = S2;
;                 r1 = r1n; w1 = w1n; k1 = k1n; q1 = q1n; n1 = n1n; r2 = r2n; w2 = w2n; k2 = k2n; g2 = g2n; n2 = n2n; v1 = v1n; v2 = v2n; cf = cfn;
	v_pk_mul_f32 v[118:119], v[104:105], v[212:213]
	v_pk_mul_f32 v[120:121], v[2:3], v[216:217]
	v_pk_fma_f32 v[118:119], v[102:103], v[210:211], v[118:119]
	v_pk_fma_f32 v[120:121], v[0:1], v[214:215], v[120:121]
	v_add_f32_e32 v122, v118, v119
	v_add_f32_e32 v123, v120, v121
	v_pk_mul_f32 v[98:99], v[2:3], v[12:13]
	v_pk_mul_f32 v[100:101], v[2:3], v[16:17]
	v_pk_fma_f32 v[98:99], v[0:1], v[10:11], v[98:99]
	v_pk_fma_f32 v[100:101], v[0:1], v[14:15], v[100:101]
	v_add_f32_e32 v106, v98, v99
	v_add_f32_e32 v107, v100, v101
	v_pk_mul_f32 v[114:115], v[18:19], v[50:51] op_sel_hi:[1,0]
	v_pk_mul_f32 v[116:117], v[20:21], v[50:51] op_sel_hi:[1,0]
	v_add_f32_dpp v106, v106, v106 quad_perm:[1,0,3,2] row_mask:0xf bank_mask:0xf bound_ctrl:1
	v_add_f32_dpp v107, v107, v107 quad_perm:[1,0,3,2] row_mask:0xf bank_mask:0xf bound_ctrl:1
	v_pk_fma_f32 v[114:115], v[0:1], v[22:23], v[114:115]
	v_pk_fma_f32 v[116:117], v[2:3], v[24:25], v[116:117]
	v_cndmask_b32_e32 v109, v107, v106, vcc
	v_mul_f32_e32 v108, v50, v52
	v_pk_mul_f32 v[110:111], v[26:27], v[50:51] op_sel:[0,1]
	v_add_f32_dpp v109, v109, v109 row_ror:2 row_mask:0xf bank_mask:0xf bound_ctrl:1
	v_pk_mul_f32 v[112:113], v[28:29], v[50:51] op_sel:[0,1]
	v_add_f32_dpp v122, v122, v122 quad_perm:[1,0,3,2] row_mask:0xf bank_mask:0xf bound_ctrl:1
	v_add_f32_dpp v109, v109, v109 row_ror:4 row_mask:0xf bank_mask:0xf bound_ctrl:1
	v_add_f32_dpp v123, v123, v123 quad_perm:[1,0,3,2] row_mask:0xf bank_mask:0xf bound_ctrl:1
	v_cndmask_b32_e32 v124, v123, v122, vcc
	v_add_f32_dpp v109, v109, v109 row_ror:8 row_mask:0xf bank_mask:0xf bound_ctrl:1
	s_nop 0
	v_add_f32_dpp v124, v124, v124 row_ror:2 row_mask:0xf bank_mask:0xf bound_ctrl:1
	v_fmac_f32_dpp v114, v109, v30 quad_perm:[0,0,2,2] row_mask:0xf bank_mask:0xf bound_ctrl:1
	v_fmac_f32_dpp v115, v109, v31 quad_perm:[0,0,2,2] row_mask:0xf bank_mask:0xf bound_ctrl:1
	v_fmac_f32_dpp v116, v109, v32 quad_perm:[0,0,2,2] row_mask:0xf bank_mask:0xf bound_ctrl:1
	v_fmac_f32_dpp v117, v109, v33 quad_perm:[0,0,2,2] row_mask:0xf bank_mask:0xf bound_ctrl:1
	v_fmac_f32_dpp v108, v109, -v53 quad_perm:[0,0,2,2] row_mask:0xf bank_mask:0xf bound_ctrl:1
	v_pk_fma_f32 v[110:111], v[114:115], v[34:35], v[110:111]
	v_pk_fma_f32 v[112:113], v[116:117], v[36:37], v[112:113]
	v_add_f32_dpp v108, v109, v108 quad_perm:[1,1,3,3] row_mask:0xf bank_mask:0xf bound_ctrl:1
	v_pk_fma_f32 v[0:1], v[38:39], v[108:109], v[110:111] op_sel_hi:[1,0,1]
	v_pk_fma_f32 v[2:3], v[40:41], v[108:109], v[112:113] op_sel_hi:[1,0,1]
	v_add_f32_dpp v124, v124, v124 row_ror:4 row_mask:0xf bank_mask:0xf bound_ctrl:1
	s_nop 0
	s_nop 0
	v_add_f32_dpp v124, v124, v124 row_ror:8 row_mask:0xf bank_mask:0xf bound_ctrl:1
	ds_write_b32 v6, v124 offset:1024
	ds_read_b128 v[178:181], v8 offset:30208
	ds_read_b128 v[182:185], v8 offset:30464
	ds_read_b128 v[186:189], v8 offset:22016
	ds_read2_b32 v[218:219], v126 offset0:96 offset1:112
	ds_read_b128 v[190:193], v8 offset:13824
	ds_read_b64 v[220:221], v7 offset:43096
	ds_read_b128 v[194:197], v8 offset:22272
	ds_read_b128 v[198:201], v8 offset:38400
	ds_read_b128 v[202:205], v8 offset:14080
	ds_read_b128 v[206:209], v8 offset:38656
	ds_read_b128 v[210:213], v8 offset:5632
	ds_read_b128 v[214:217], v8 offset:5888
	s_waitcnt lgkmcnt(15)
	v_pk_mul_f32 v[118:119], v[116:117], v[44:45]
	v_pk_mul_f32 v[120:121], v[2:3], v[48:49]
	v_pk_fma_f32 v[118:119], v[114:115], v[42:43], v[118:119]
	v_pk_fma_f32 v[120:121], v[0:1], v[46:47], v[120:121]
	v_add_f32_e32 v122, v118, v119
	v_add_f32_e32 v123, v120, v121
	v_pk_mul_f32 v[98:99], v[2:3], v[56:57]
	v_pk_mul_f32 v[100:101], v[2:3], v[60:61]
	v_pk_fma_f32 v[98:99], v[0:1], v[54:55], v[98:99]
	v_pk_fma_f32 v[100:101], v[0:1], v[58:59], v[100:101]
	v_add_f32_e32 v106, v98, v99
	v_add_f32_e32 v107, v100, v101
	v_pk_mul_f32 v[102:103], v[62:63], v[94:95] op_sel_hi:[1,0]
	v_pk_mul_f32 v[104:105], v[64:65], v[94:95] op_sel_hi:[1,0]
	v_add_f32_dpp v106, v106, v106 quad_perm:[1,0,3,2] row_mask:0xf bank_mask:0xf bound_ctrl:1
	v_add_f32_dpp v107, v107, v107 quad_perm:[1,0,3,2] row_mask:0xf bank_mask:0xf bound_ctrl:1
	v_pk_fma_f32 v[102:103], v[0:1], v[66:67], v[102:103]
	v_pk_fma_f32 v[104:105], v[2:3], v[68:69], v[104:105]
	v_cndmask_b32_e32 v109, v107, v106, vcc
	v_mul_f32_e32 v108, v94, v96
	v_pk_mul_f32 v[110:111], v[70:71], v[94:95] op_sel:[0,1]
	v_add_f32_dpp v109, v109, v109 row_ror:2 row_mask:0xf bank_mask:0xf bound_ctrl:1
	v_pk_mul_f32 v[112:113], v[72:73], v[94:95] op_sel:[0,1]
	v_add_f32_dpp v122, v122, v122 quad_perm:[1,0,3,2] row_mask:0xf bank_mask:0xf bound_ctrl:1
	v_add_f32_dpp v109, v109, v109 row_ror:4 row_mask:0xf bank_mask:0xf bound_ctrl:1
	v_add_f32_dpp v123, v123, v123 quad_perm:[1,0,3,2] row_mask:0xf bank_mask:0xf bound_ctrl:1
	v_cndmask_b32_e32 v124, v123, v122, vcc
	v_add_f32_dpp v109, v109, v109 row_ror:8 row_mask:0xf bank_mask:0xf bound_ctrl:1
	s_nop 0
	v_add_f32_dpp v124, v124, v124 row_ror:2 row_mask:0xf bank_mask:0xf bound_ctrl:1
	v_fmac_f32_dpp v102, v109, v74 quad_perm:[0,0,2,2] row_mask:0xf bank_mask:0xf bound_ctrl:1
	v_fmac_f32_dpp v103, v109, v75 quad_perm:[0,0,2,2] row_mask:0xf bank_mask:0xf bound_ctrl:1
	v_fmac_f32_dpp v104, v109, v76 quad_perm:[0,0,2,2] row_mask:0xf bank_mask:0xf bound_ctrl:1
	v_fmac_f32_dpp v105, v109, v77 quad_perm:[0,0,2,2] row_mask:0xf bank_mask:0xf bound_ctrl:1
	v_fmac_f32_dpp v108, v109, -v97 quad_perm:[0,0,2,2] row_mask:0xf bank_mask:0xf bound_ctrl:1
	v_pk_fma_f32 v[110:111], v[102:103], v[78:79], v[110:111]
	v_pk_fma_f32 v[112:113], v[104:105], v[80:81], v[112:113]
	v_add_f32_dpp v108, v109, v108 quad_perm:[1,1,3,3] row_mask:0xf bank_mask:0xf bound_ctrl:1
	v_pk_fma_f32 v[0:1], v[82:83], v[108:109], v[110:111] op_sel_hi:[1,0,1]
	v_pk_fma_f32 v[2:3], v[84:85], v[108:109], v[112:113] op_sel_hi:[1,0,1]
	v_add_f32_dpp v124, v124, v124 row_ror:4 row_mask:0xf bank_mask:0xf bound_ctrl:1
	s_nop 0
	s_nop 0
	v_add_f32_dpp v124, v124, v124 row_ror:8 row_mask:0xf bank_mask:0xf bound_ctrl:1
	ds_write_b32 v6, v124 offset:1152
	ds_read_b128 v[10:13], v8 offset:30720
	ds_read_b128 v[14:17], v8 offset:30976
	ds_read_b128 v[18:21], v8 offset:22528
	ds_read2_b32 v[50:51], v126 offset0:128 offset1:144
	ds_read_b128 v[22:25], v8 offset:14336
	ds_read_b64 v[52:53], v7 offset:43104
	ds_read_b128 v[26:29], v8 offset:22784
	ds_read_b128 v[30:33], v8 offset:38912
	ds_read_b128 v[34:37], v8 offset:14592
	ds_read_b128 v[38:41], v8 offset:39168
	ds_read_b128 v[42:45], v8 offset:6144
	ds_read_b128 v[46:49], v8 offset:6400
	s_waitcnt lgkmcnt(15)
; template <int CTRL> __device__ __forceinline__ float dppf(float x) { return __builtin_bit_cast(float, __builtin_amdgcn_mov_dpp(__builtin_bit_cast(int, x), CTRL, 0xf, 0xf, true)); }
; __device__ __forceinline__ float dot4(const f32x4& a, const f32x4& b) {
;     f32x2 t = __builtin_shufflevector(a, a, 0, 1) * __builtin_shufflevector(b, b, 0, 1);
;     t = __builtin_shufflevector(a, a, 2, 3) * __builtin_shufflevector(b, b, 2, 3) + t;
;     return t[0] + t[1];
; }
; __device__ __forceinline__ void reduce16x2(float& a, float& b) {
;     a += dppf<0xB1>(a); b += dppf<0xB1>(b); a += dppf<0x4E>(a); b += dppf<0x4E>(b);
;     a += dppf<0x141>(a); b += dppf<0x141>(b); a += dppf<0x140>(a); b += dppf<0x140>(b);
; }
; __device__ __forceinline__ void scan_unit(const Params& p, int unit) {
;     ...
;             for (int pr = 0; pr < SC_TC / 2; ++pr) {
;                 const int sn = 2 * pr + 2;
;                 const f32x4 r1n = SC_LD(0, sn), w1n = SC_LD(1, sn), k1n = SC_LD(2, sn), q1n = SC_LD(3, sn), n1n = SC_LD(4, sn);
;                 const f32x4 r2n = SC_LD(0, sn + 1), w2n = SC_LD(1, sn + 1), k2n = SC_LD(2, sn + 1), g2n = SC_LD(3, sn + 1), n2n = SC_LD(4, sn + 1);
;                 const float v1n = buf[SC_VOFF + sn * 16 + rl], v2n = buf[SC_VOFF + (sn + 1) * 16 + rl];
;                 const f32x2 cfn = *(const f32x2*)(buf + SC_COFF + (pr + 1) * 2);
;                 __builtin_amdgcn_sched_barrier(0x7);
;                 float d1 = dot4(S, q1), e2 = dot4(S, g2);
;                 const f32x4 t1 = S * w1 + v1 * k1;
;                 reduce16x2(d1, e2);
;                 const float d2 = e2 + v1 * cf[0] - d1 * cf[1];
;                 const f32x4 S1 = t1 + d1 * n1;
;                 const f32x4 S2 = (S1 * w2 + v2 * k2) + d2 * n2;
;                 float y1 = dot4(S1, r1), y2 = dot4(S2, r2);
;                 y1 += dppf<0xB1>(y1); y2 += dppf<0xB1>(y2);
;                 float yz = odd_lane ? y2 : y1;
;                 yz += dppf<0x122>(yz); yz += dppf<0x124>(yz); yz += dppf<0x128>(yz);
;                 yb[(2 * pr) * 16 + yoff] = yz;
;                 S = S2;
;                 r1 = r1n; w1 = w1n; k1 = k1n; q1 = q1n; n1 = n1n; r2 = r2n; w2 = w2n; k2 = k2n; g2 = g2n; n2 = n2n; v1 = v1n; v2 = v2n; cf = cfn;
	v_pk_mul_f32 v[118:119], v[104:105], v[88:89]
	v_pk_mul_f32 v[120:121], v[2:3], v[92:93]
	v_pk_fma_f32 v[118:119], v[102:103], v[86:87], v[118:119]
	v_pk_fma_f32 v[120:121], v[0:1], v[90:91], v[120:121]
	v_add_f32_e32 v122, v118, v119
	v_add_f32_e32 v123, v120, v121
	v_pk_mul_f32 v[98:99], v[2:3], v[180:181]
	v_pk_mul_f32 v[100:101], v[2:3], v[184:185]
	v_pk_fma_f32 v[98:99], v[0:1], v[178:179], v[98:99]
	v_pk_fma_f32 v[100:101], v[0:1], v[182:183], v[100:101]
	v_add_f32_e32 v106, v98, v99
	v_add_f32_e32 v107, v100, v101
	v_pk_mul_f32 v[114:115], v[186:187], v[218:219] op_sel_hi:[1,0]
	v_pk_mul_f32 v[116:117], v[188:189], v[218:219] op_sel_hi:[1,0]
	v_add_f32_dpp v106, v106, v106 quad_perm:[1,0,3,2] row_mask:0xf bank_mask:0xf bound_ctrl:1
	v_add_f32_dpp v107, v107, v107 quad_perm:[1,0,3,2] row_mask:0xf bank_mask:0xf bound_ctrl:1
	v_pk_fma_f32 v[114:115], v[0:1], v[190:191], v[114:115]
	v_pk_fma_f32 v[116:117], v[2:3], v[192:193], v[116:117]
	v_cndmask_b32_e32 v109, v107, v106, vcc
	v_mul_f32_e32 v108, v218, v220
	v_pk_mul_f32 v[110:111], v[194:195], v[218:219] op_sel:[0,1]
	v_add_f32_dpp v109, v109, v109 row_ror:2 row_mask:0xf bank_mask:0xf bound_ctrl:1
	v_pk_mul_f32 v[112:113], v[196:197], v[218:219] op_sel:[0,1]
	v_add_f32_dpp v122, v122, v122 quad_perm:[1,0,3,2] row_mask:0xf bank_mask:0xf bound_ctrl:1
	v_add_f32_dpp v109, v109, v109 row_ror:4 row_mask:0xf bank_mask:0xf bound_ctrl:1
	v_add_f32_dpp v123, v123, v123 quad_perm:[1,0,3,2] row_mask:0xf bank_mask:0xf bound_ctrl:1
	v_cndmask_b32_e32 v124, v123, v122, vcc
	v_add_f32_dpp v109, v109, v109 row_ror:8 row_mask:0xf bank_mask:0xf bound_ctrl:1
	s_nop 0
	v_add_f32_dpp v124, v124, v124 row_ror:2 row_mask:0xf bank_mask:0xf bound_ctrl:1
	v_fmac_f32_dpp v114, v109, v198 quad_perm:[0,0,2,2] row_mask:0xf bank_mask:0xf bound_ctrl:1
	v_fmac_f32_dpp v115, v109, v199 quad_perm:[0,0,2,2] row_mask:0xf bank_mask:0xf bound_ctrl:1
	v_fmac_f32_dpp v116, v109, v200 quad_perm:[0,0,2,2] row_mask:0xf bank_mask:0xf bound_ctrl:1
	v_fmac_f32_dpp v117, v109, v201 quad_perm:[0,0,2,2] row_mask:0xf bank_mask:0xf bound_ctrl:1
	v_fmac_f32_dpp v108, v109, -v221 quad_perm:[0,0,2,2] row_mask:0xf bank_mask:0xf bound_ctrl:1
	v_pk_fma_f32 v[110:111], v[114:115], v[202:203], v[110:111]
	v_pk_fma_f32 v[112:113], v[116:117], v[204:205], v[112:113]
	v_add_f32_dpp v108, v109, v108 quad_perm:[1,1,3,3] row_mask:0xf bank_mask:0xf bound_ctrl:1
	v_pk_fma_f32 v[0:1], v[206:207], v[108:109], v[110:111] op_sel_hi:[1,0,1]
	v_pk_fma_f32 v[2:3], v[208:209], v[108:109], v[112:113] op_sel_hi:[1,0,1]
	v_add_f32_dpp v124, v124, v124 row_ror:4 row_mask:0xf bank_mask:0xf bound_ctrl:1
	s_nop 0
	s_nop 0
	v_add_f32_dpp v124, v124, v124 row_ror:8 row_mask:0xf bank_mask:0xf bound_ctrl:1
	ds_write_b32 v6, v124 offset:1280
	ds_read_b128 v[54:57], v8 offset:31232
	ds_read_b128 v[58:61], v8 offset:31488
	ds_read_b128 v[62:65], v8 offset:23040
	ds_read2_b32 v[94:95], v126 offset0:160 offset1:176
	ds_read_b128 v[66:69], v8 offset:14848
	ds_read_b64 v[96:97], v7 offset:43112
	ds_read_b128 v[70:73], v8 offset:23296
	ds_read_b128 v[74:77], v8 offset:39424
	ds_read_b128 v[78:81], v8 offset:15104
	ds_read_b128 v[82:85], v8 offset:39680
	ds_read_b128 v[86:89], v8 offset:6656
	ds_read_b128 v[90:93], v8 offset:6912
	s_waitcnt lgkmcnt(15)
	v_pk_mul_f32 v[118:119], v[116:117], v[212:213]
	v_pk_mul_f32 v[120:121], v[2:3], v[216:217]
	v_pk_fma_f32 v[118:119], v[114:115], v[210:211], v[118:119]
	v_pk_fma_f32 v[120:121], v[0:1], v[214:215], v[120:121]
	v_add_f32_e32 v122, v118, v119
	v_add_f32_e32 v123, v120, v121
	v_pk_mul_f32 v[98:99], v[2:3], v[12:13]
	v_pk_mul_f32 v[100:101], v[2:3], v[16:17]
	v_pk_fma_f32 v[98:99], v[0:1], v[10:11], v[98:99]
	v_pk_fma_f32 v[100:101], v[0:1], v[14:15], v[100:101]
	v_add_f32_e32 v106, v98, v99
	v_add_f32_e32 v107, v100, v101
	v_pk_mul_f32 v[102:103], v[18:19], v[50:51] op_sel_hi:[1,0]
	v_pk_mul_f32 v[104:105], v[20:21], v[50:51] op_sel_hi:[1,0]
	v_add_f32_dpp v106, v106, v106 quad_perm:[1,0,3,2] row_mask:0xf bank_mask:0xf bound_ctrl:1
	v_add_f32_dpp v107, v107, v107 quad_perm:[1,0,3,2] row_mask:0xf bank_mask:0xf bound_ctrl:1
	v_pk_fma_f32 v[102:103], v[0:1], v[22:23], v[102:103]
	v_pk_fma_f32 v[104:105], v[2:3], v[24:25], v[104:105]
	v_cndmask_b32_e32 v109, v107, v106, vcc
	v_mul_f32_e32 v108, v50, v52
	v_pk_mul_f32 v[110:111], v[26:27], v[50:51] op_sel:[0,1]
	v_add_f32_dpp v109, v109, v109 row_ror:2 row_mask:0xf bank_mask:0xf bound_ctrl:1
	v_pk_mul_f32 v[112:113], v[28:29], v[50:51] op_sel:[0,1]
	v_add_f32_dpp v122, v122, v122 quad_perm:[1,0,3,2] row_mask:0xf bank_mask:0xf bound_ctrl:1
	v_add_f32_dpp v109, v109, v109 row_ror:4 row_mask:0xf bank_mask:0xf bound_ctrl:1
	v_add_f32_dpp v123, v123, v123 quad_perm:[1,0,3,2] row_mask:0xf bank_mask:0xf bound_ctrl:1
	v_cndmask_b32_e32 v124, v123, v122, vcc
	v_add_f32_dpp v109, v109, v109 row_ror:8 row_mask:0xf bank_mask:0xf bound_ctrl:1
	s_nop 0
	v_add_f32_dpp v124, v124, v124 row_ror:2 row_mask:0xf bank_mask:0xf bound_ctrl:1
	v_fmac_f32_dpp v102, v109, v30 quad_perm:[0,0,2,2] row_mask:0xf bank_mask:0xf bound_ctrl:1
	v_fmac_f32_dpp v103, v109, v31 quad_perm:[0,0,2,2] row_mask:0xf bank_mask:0xf bound_ctrl:1
	v_fmac_f32_dpp v104, v109, v32 quad_perm:[0,0,2,2] row_mask:0xf bank_mask:0xf bound_ctrl:1
	v_fmac_f32_dpp v105, v109, v33 quad_perm:[0,0,2,2] row_mask:0xf bank_mask:0xf bound_ctrl:1
	v_fmac_f32_dpp v108, v109, -v53 quad_perm:[0,0,2,2] row_mask:0xf bank_mask:0xf bound_ctrl:1
	v_pk_fma_f32 v[110:111], v[102:103], v[34:35], v[110:111]
	v_pk_fma_f32 v[112:113], v[104:105], v[36:37], v[112:113]
	v_add_f32_dpp v108, v109, v108 quad_perm:[1,1,3,3] row_mask:0xf bank_mask:0xf bound_ctrl:1
	v_pk_fma_f32 v[0:1], v[38:39], v[108:109], v[110:111] op_sel_hi:[1,0,1]
	v_pk_fma_f32 v[2:3], v[40:41], v[108:109], v[112:113] op_sel_hi:[1,0,1]
	v_add_f32_dpp v124, v124, v124 row_ror:4 row_mask:0xf bank_mask:0xf bound_ctrl:1
	s_nop 0
	s_nop 0
	v_add_f32_dpp v124, v124, v124 row_ror:8 row_mask:0xf bank_mask:0xf bound_ctrl:1
	ds_write_b32 v6, v124 offset:1408
	ds_read_b128 v[178:181], v8 offset:31744
	ds_read_b128 v[182:185], v8 offset:32000
	ds_read_b128 v[186:189], v8 offset:23552
	ds_read2_b32 v[218:219], v126 offset0:192 offset1:208
	ds_read_b128 v[190:193], v8 offset:15360
	ds_read_b64 v[220:221], v7 offset:43120
	ds_read_b128 v[194:197], v8 offset:23808
	ds_read_b128 v[198:201], v8 offset:39936
	ds_read_b128 v[202:205], v8 offset:15616
	ds_read_b128 v[206:209], v8 offset:40192
	ds_read_b128 v[210:213], v8 offset:7168
	ds_read_b128 v[214:217], v8 offset:7424
	s_waitcnt lgkmcnt(15)
; template <int CTRL> __device__ __forceinline__ float dppf(float x) { return __builtin_bit_cast(float, __builtin_amdgcn_mov_dpp(__builtin_bit_cast(int, x), CTRL, 0xf, 0xf, true)); }
; __device__ __forceinline__ float dot4(const f32x4& a, const f32x4& b) {
;     f32x2 t = __builtin_shufflevector(a, a, 0, 1) * __builtin_shufflevector(b, b, 0, 1);
;     t = __builtin_shufflevector(a, a, 2, 3) * __builtin_shufflevector(b, b, 2, 3) + t;
;     return t[0] + t[1];
; }
; __device__ __forceinline__ void reduce16x2(float& a, float& b) {
;     a += dppf<0xB1>(a); b += dppf<0xB1>(b); a += dppf<0x4E>(a); b += dppf<0x4E>(b);
;     a += dppf<0x141>(a); b += dppf<0x141>(b); a += dppf<0x140>(a); b += dppf<0x140>(b);
; }
; __device__ __forceinline__ void scan_unit(const Params& p, int unit) {
;     ...
;             for (int pr = 0; pr < SC_TC / 2; ++pr) {
;                 const int sn = 2 * pr + 2;
;                 const f32x4 r1n = SC_LD(0, sn), w1n = SC_LD(1, sn), k1n = SC_LD(2, sn), q1n = SC_LD(3, sn), n1n = SC_LD(4, sn);
;                 const f32x4 r2n = SC_LD(0, sn + 1), w2n = SC_LD(1, sn + 1), k2n = SC_LD(2, sn + 1), g2n = SC_LD(3, sn + 1), n2n = SC_LD(4, sn + 1);
;                 const float v1n = buf[SC_VOFF + sn * 16 + rl], v2n = buf[SC_VOFF + (sn + 1) * 16 + rl];
;                 const f32x2 cfn = *(const f32x2*)(buf + SC_COFF + (pr + 1) * 2);
;                 __builtin_amdgcn_sched_barrier(0x7);
;                 float d1 = dot4(S, q1), e2 = dot4(S, g2);
;                 const f32x4 t1 = S * w1 + v1 * k1;
;                 reduce16x2(d1, e2);
;                 const float d2 = e2 + v1 * cf[0] - d1 * cf[1];
;                 const f32x4 S1 = t1 + d1 * n1;
;                 const f32x4 S2 = (S1 * w2 + v2 * k2) + d2 * n2;
;                 float y1 = dot4(S1, r1), y2 = dot4(S2, r2);
;                 y1 += dppf<0xB1>(y1); y2 += dppf<0xB1>(y2);
;                 float yz = odd_lane ? y2 : y1;
;                 yz += dppf<0x122>(yz); yz += dppf<0x124>(yz); yz += dppf<0x128>(yz);
;                 yb[(2 * pr) * 16 + yoff] = yz;
;                 S = S2;
;                 r1 = r1n; w1 = w1n; k1 = k1n; q1 = q1n; n1 = n1n; r2 = r2n; w2 = w2n; k2 = k2n; g2 = g2n; n2 = n2n; v1 = v1n; v2 = v2n; cf = cfn;
	v_pk_mul_f32 v[118:119], v[104:105], v[44:45]
	v_pk_mul_f32 v[120:121], v[2:3], v[48:49]
	v_pk_fma_f32 v[118:119], v[102:103], v[42:43], v[118:119]
	v_pk_fma_f32 v[120:121], v[0:1], v[46:47], v[120:121]
	v_add_f32_e32 v122, v118, v119
	v_add_f32_e32 v123, v120, v121
	v_pk_mul_f32 v[98:99], v[2:3], v[56:57]
	v_pk_mul_f32 v[100:101], v[2:3], v[60:61]
	v_pk_fma_f32 v[98:99], v[0:1], v[54:55], v[98:99]
	v_pk_fma_f32 v[100:101], v[0:1], v[58:59], v[100:101]
	v_add_f32_e32 v106, v98, v99
	v_add_f32_e32 v107, v100, v101
	v_pk_mul_f32 v[114:115], v[62:63], v[94:95] op_sel_hi:[1,0]
	v_pk_mul_f32 v[116:117], v[64:65], v[94:95] op_sel_hi:[1,0]
	v_add_f32_dpp v106, v106, v106 quad_perm:[1,0,3,2] row_mask:0xf bank_mask:0xf bound_ctrl:1
	v_add_f32_dpp v107, v107, v107 quad_perm:[1,0,3,2] row_mask:0xf bank_mask:0xf bound_ctrl:1
	v_pk_fma_f32 v[114:115], v[0:1], v[66:67], v[114:115]
	v_pk_fma_f32 v[116:117], v[2:3], v[68:69], v[116:117]
	v_cndmask_b32_e32 v109, v107, v106, vcc
	v_mul_f32_e32 v108, v94, v96
	v_pk_mul_f32 v[110:111], v[70:71], v[94:95] op_sel:[0,1]
	v_add_f32_dpp v109, v109, v109 row_ror:2 row_mask:0xf bank_mask:0xf bound_ctrl:1
	v_pk_mul_f32 v[112:113], v[72:73], v[94:95] op_sel:[0,1]
	v_add_f32_dpp v122, v122, v122 quad_perm:[1,0,3,2] row_mask:0xf bank_mask:0xf bound_ctrl:1
	v_add_f32_dpp v109, v109, v109 row_ror:4 row_mask:0xf bank_mask:0xf bound_ctrl:1
	v_add_f32_dpp v123, v123, v123 quad_perm:[1,0,3,2] row_mask:0xf bank_mask:0xf bound_ctrl:1
	v_cndmask_b32_e32 v124, v123, v122, vcc
	v_add_f32_dpp v109, v109, v109 row_ror:8 row_mask:0xf bank_mask:0xf bound_ctrl:1
	s_nop 0
	v_add_f32_dpp v124, v124, v124 row_ror:2 row_mask:0xf bank_mask:0xf bound_ctrl:1
	v_fmac_f32_dpp v114, v109, v74 quad_perm:[0,0,2,2] row_mask:0xf bank_mask:0xf bound_ctrl:1
	v_fmac_f32_dpp v115, v109, v75 quad_perm:[0,0,2,2] row_mask:0xf bank_mask:0xf bound_ctrl:1
	v_fmac_f32_dpp v116, v109, v76 quad_perm:[0,0,2,2] row_mask:0xf bank_mask:0xf bound_ctrl:1
	v_fmac_f32_dpp v117, v109, v77 quad_perm:[0,0,2,2] row_mask:0xf bank_mask:0xf bound_ctrl:1
	v_fmac_f32_dpp v108, v109, -v97 quad_perm:[0,0,2,2] row_mask:0xf bank_mask:0xf bound_ctrl:1
	v_pk_fma_f32 v[110:111], v[114:115], v[78:79], v[110:111]
	v_pk_fma_f32 v[112:113], v[116:117], v[80:81], v[112:113]
	v_add_f32_dpp v108, v109, v108 quad_perm:[1,1,3,3] row_mask:0xf bank_mask:0xf bound_ctrl:1
	v_pk_fma_f32 v[0:1], v[82:83], v[108:109], v[110:111] op_sel_hi:[1,0,1]
	v_pk_fma_f32 v[2:3], v[84:85], v[108:109], v[112:113] op_sel_hi:[1,0,1]
	v_add_f32_dpp v124, v124, v124 row_ror:4 row_mask:0xf bank_mask:0xf bound_ctrl:1
	s_nop 0
	s_nop 0
	v_add_f32_dpp v124, v124, v124 row_ror:8 row_mask:0xf bank_mask:0xf bound_ctrl:1
	ds_write_b32 v6, v124 offset:1536
	ds_read_b128 v[10:13], v8 offset:32256
	ds_read_b128 v[14:17], v8 offset:32512
	ds_read_b128 v[18:21], v8 offset:24064
	ds_read2_b32 v[50:51], v126 offset0:224 offset1:240
	ds_read_b128 v[22:25], v8 offset:15872
	ds_read_b64 v[52:53], v7 offset:43128
	ds_read_b128 v[26:29], v8 offset:24320
	ds_read_b128 v[30:33], v8 offset:40448
	ds_read_b128 v[34:37], v8 offset:16128
	ds_read_b128 v[38:41], v8 offset:40704
	ds_read_b128 v[42:45], v8 offset:7680
	ds_read_b128 v[46:49], v8 offset:7936
	s_waitcnt lgkmcnt(15)
	v_pk_mul_f32 v[118:119], v[116:117], v[88:89]
	v_pk_mul_f32 v[120:121], v[2:3], v[92:93]
	v_pk_fma_f32 v[118:119], v[114:115], v[86:87], v[118:119]
	v_pk_fma_f32 v[120:121], v[0:1], v[90:91], v[120:121]
	v_add_f32_e32 v122, v118, v119
	v_add_f32_e32 v123, v120, v121
	v_pk_mul_f32 v[98:99], v[2:3], v[180:181]
	v_pk_mul_f32 v[100:101], v[2:3], v[184:185]
	v_pk_fma_f32 v[98:99], v[0:1], v[178:179], v[98:99]
	v_pk_fma_f32 v[100:101], v[0:1], v[182:183], v[100:101]
	v_add_f32_e32 v106, v98, v99
	v_add_f32_e32 v107, v100, v101
	v_pk_mul_f32 v[102:103], v[186:187], v[218:219] op_sel_hi:[1,0]
	v_pk_mul_f32 v[104:105], v[188:189], v[218:219] op_sel_hi:[1,0]
	v_add_f32_dpp v106, v106, v106 quad_perm:[1,0,3,2] row_mask:0xf bank_mask:0xf bound_ctrl:1
	v_add_f32_dpp v107, v107, v107 quad_perm:[1,0,3,2] row_mask:0xf bank_mask:0xf bound_ctrl:1
	v_pk_fma_f32 v[102:103], v[0:1], v[190:191], v[102:103]
	v_pk_fma_f32 v[104:105], v[2:3], v[192:193], v[104:105]
	v_cndmask_b32_e32 v109, v107, v106, vcc
	v_mul_f32_e32 v108, v218, v220
	v_pk_mul_f32 v[110:111], v[194:195], v[218:219] op_sel:[0,1]
	v_add_f32_dpp v109, v109, v109 row_ror:2 row_mask:0xf bank_mask:0xf bound_ctrl:1
	v_pk_mul_f32 v[112:113], v[196:197], v[218:219] op_sel:[0,1]
	v_add_f32_dpp v122, v122, v122 quad_perm:[1,0,3,2] row_mask:0xf bank_mask:0xf bound_ctrl:1
	v_add_f32_dpp v109, v109, v109 row_ror:4 row_mask:0xf bank_mask:0xf bound_ctrl:1
	v_add_f32_dpp v123, v123, v123 quad_perm:[1,0,3,2] row_mask:0xf bank_mask:0xf bound_ctrl:1
	v_cndmask_b32_e32 v124, v123, v122, vcc
	v_add_f32_dpp v109, v109, v109 row_ror:8 row_mask:0xf bank_mask:0xf bound_ctrl:1
	s_nop 0
	v_add_f32_dpp v124, v124, v124 row_ror:2 row_mask:0xf bank_mask:0xf bound_ctrl:1
	v_fmac_f32_dpp v102, v109, v198 quad_perm:[0,0,2,2] row_mask:0xf bank_mask:0xf bound_ctrl:1
	v_fmac_f32_dpp v103, v109, v199 quad_perm:[0,0,2,2] row_mask:0xf bank_mask:0xf bound_ctrl:1
	v_fmac_f32_dpp v104, v109, v200 quad_perm:[0,0,2,2] row_mask:0xf bank_mask:0xf bound_ctrl:1
	v_fmac_f32_dpp v105, v109, v201 quad_perm:[0,0,2,2] row_mask:0xf bank_mask:0xf bound_ctrl:1
	v_fmac_f32_dpp v108, v109, -v221 quad_perm:[0,0,2,2] row_mask:0xf bank_mask:0xf bound_ctrl:1
	v_pk_fma_f32 v[110:111], v[102:103], v[202:203], v[110:111]
	v_pk_fma_f32 v[112:113], v[104:105], v[204:205], v[112:113]
	v_add_f32_dpp v108, v109, v108 quad_perm:[1,1,3,3] row_mask:0xf bank_mask:0xf bound_ctrl:1
	v_pk_fma_f32 v[0:1], v[206:207], v[108:109], v[110:111] op_sel_hi:[1,0,1]
	v_pk_fma_f32 v[2:3], v[208:209], v[108:109], v[112:113] op_sel_hi:[1,0,1]
	v_add_f32_dpp v124, v124, v124 row_ror:4 row_mask:0xf bank_mask:0xf bound_ctrl:1
	s_nop 0
	s_nop 0
	v_add_f32_dpp v124, v124, v124 row_ror:8 row_mask:0xf bank_mask:0xf bound_ctrl:1
	ds_write_b32 v6, v124 offset:1664
	s_waitcnt lgkmcnt(15)
; template <int CTRL> __device__ __forceinline__ float dppf(float x) { return __builtin_bit_cast(float, __builtin_amdgcn_mov_dpp(__builtin_bit_cast(int, x), CTRL, 0xf, 0xf, true)); }
; __device__ __forceinline__ void scan_unit(const Params& p, int unit) {
;     ...
;             for (int pr = 0; pr < SC_TC / 2; ++pr) {
;                 const int sn = 2 * pr + 2;
;                 const f32x4 r1n = SC_LD(0, sn), w1n = SC_LD(1, sn), k1n = SC_LD(2, sn), q1n = SC_LD(3, sn), n1n = SC_LD(4, sn);
;                 const f32x4 r2n = SC_LD(0, sn + 1), w2n = SC_LD(1, sn + 1), k2n = SC_LD(2, sn + 1), g2n = SC_LD(3, sn + 1), n2n = SC_LD(4, sn + 1);
;                 const float v1n = buf[SC_VOFF + sn * 16 + rl], v2n = buf[SC_VOFF + (sn + 1) * 16 + rl];
;                 const f32x2 cfn = *(const f32x2*)(buf + SC_COFF + (pr + 1) * 2);
;                 __builtin_amdgcn_sched_barrier(0x7);
;                 float d1 = dot4(S, q1), e2 = dot4(S, g2);
;                 const f32x4 t1 = S * w1 + v1 * k1;
;                 reduce16x2(d1, e2);
;                 const float d2 = e2 + v1 * cf[0] - d1 * cf[1];
;                 const f32x4 S1 = t1 + d1 * n1;
;                 const f32x4 S2 = (S1 * w2 + v2 * k2) + d2 * n2;
;                 float y1 = dot4(S1, r1), y2 = dot4(S2, r2);
;                 y1 += dppf<0xB1>(y1); y2 += dppf<0xB1>(y2);
;                 float yz = odd_lane ? y2 : y1;
;                 yz += dppf<0x122>(yz); yz += dppf<0x124>(yz); yz += dppf<0x128>(yz);
;                 yb[(2 * pr) * 16 + yoff] = yz;
;                 S = S2;
;                 r1 = r1n; w1 = w1n; k1 = k1n; q1 = q1n; n1 = n1n; r2 = r2n; w2 = w2n; k2 = k2n; g2 = g2n; n2 = n2n; v1 = v1n; v2 = v2n; cf = cfn;
;             }
;     ...
;             __syncthreads();
;         }
	v_pk_mul_f32 v[118:119], v[104:105], v[212:213]
	s_waitcnt lgkmcnt(14)
	v_pk_mul_f32 v[120:121], v[2:3], v[216:217]
	v_pk_fma_f32 v[118:119], v[102:103], v[210:211], v[118:119]
	v_pk_fma_f32 v[120:121], v[0:1], v[214:215], v[120:121]
	v_add_f32_e32 v122, v118, v119
	v_add_f32_e32 v123, v120, v121
	s_waitcnt lgkmcnt(12)
	v_pk_mul_f32 v[98:99], v[2:3], v[12:13]
	s_waitcnt lgkmcnt(11)
	v_pk_mul_f32 v[100:101], v[2:3], v[16:17]
	v_pk_fma_f32 v[98:99], v[0:1], v[10:11], v[98:99]
	v_pk_fma_f32 v[100:101], v[0:1], v[14:15], v[100:101]
	v_add_f32_e32 v106, v98, v99
	v_add_f32_e32 v107, v100, v101
	s_waitcnt lgkmcnt(9)
	v_pk_mul_f32 v[114:115], v[18:19], v[50:51] op_sel_hi:[1,0]
	v_pk_mul_f32 v[116:117], v[20:21], v[50:51] op_sel_hi:[1,0]
	v_add_f32_dpp v106, v106, v106 quad_perm:[1,0,3,2] row_mask:0xf bank_mask:0xf bound_ctrl:1
	v_add_f32_dpp v107, v107, v107 quad_perm:[1,0,3,2] row_mask:0xf bank_mask:0xf bound_ctrl:1
	s_waitcnt lgkmcnt(8)
	v_pk_fma_f32 v[114:115], v[0:1], v[22:23], v[114:115]
	v_pk_fma_f32 v[116:117], v[2:3], v[24:25], v[116:117]
	v_cndmask_b32_e32 v109, v107, v106, vcc
	s_waitcnt lgkmcnt(7)
	v_mul_f32_e32 v108, v50, v52
	s_waitcnt lgkmcnt(6)
	v_pk_mul_f32 v[110:111], v[26:27], v[50:51] op_sel:[0,1]
	v_add_f32_dpp v109, v109, v109 row_ror:2 row_mask:0xf bank_mask:0xf bound_ctrl:1
	v_pk_mul_f32 v[112:113], v[28:29], v[50:51] op_sel:[0,1]
	v_add_f32_dpp v122, v122, v122 quad_perm:[1,0,3,2] row_mask:0xf bank_mask:0xf bound_ctrl:1
	v_add_f32_dpp v109, v109, v109 row_ror:4 row_mask:0xf bank_mask:0xf bound_ctrl:1
	v_add_f32_dpp v123, v123, v123 quad_perm:[1,0,3,2] row_mask:0xf bank_mask:0xf bound_ctrl:1
	v_cndmask_b32_e32 v124, v123, v122, vcc
	v_add_f32_dpp v109, v109, v109 row_ror:8 row_mask:0xf bank_mask:0xf bound_ctrl:1
	s_nop 0
	v_add_f32_dpp v124, v124, v124 row_ror:2 row_mask:0xf bank_mask:0xf bound_ctrl:1
	s_waitcnt lgkmcnt(5)
	v_fmac_f32_dpp v114, v109, v30 quad_perm:[0,0,2,2] row_mask:0xf bank_mask:0xf bound_ctrl:1
	v_fmac_f32_dpp v115, v109, v31 quad_perm:[0,0,2,2] row_mask:0xf bank_mask:0xf bound_ctrl:1
	v_fmac_f32_dpp v116, v109, v32 quad_perm:[0,0,2,2] row_mask:0xf bank_mask:0xf bound_ctrl:1
	v_fmac_f32_dpp v117, v109, v33 quad_perm:[0,0,2,2] row_mask:0xf bank_mask:0xf bound_ctrl:1
	v_fmac_f32_dpp v108, v109, -v53 quad_perm:[0,0,2,2] row_mask:0xf bank_mask:0xf bound_ctrl:1
	s_waitcnt lgkmcnt(4)
	v_pk_fma_f32 v[110:111], v[114:115], v[34:35], v[110:111]
	v_pk_fma_f32 v[112:113], v[116:117], v[36:37], v[112:113]
	v_add_f32_dpp v108, v109, v108 quad_perm:[1,1,3,3] row_mask:0xf bank_mask:0xf bound_ctrl:1
	s_waitcnt lgkmcnt(3)
	v_pk_fma_f32 v[0:1], v[38:39], v[108:109], v[110:111] op_sel_hi:[1,0,1]
	v_pk_fma_f32 v[2:3], v[40:41], v[108:109], v[112:113] op_sel_hi:[1,0,1]
	v_add_f32_dpp v124, v124, v124 row_ror:4 row_mask:0xf bank_mask:0xf bound_ctrl:1
	s_nop 0
	s_nop 0
	v_add_f32_dpp v124, v124, v124 row_ror:8 row_mask:0xf bank_mask:0xf bound_ctrl:1
	ds_write_b32 v6, v124 offset:1792
	s_waitcnt lgkmcnt(3)
	v_pk_mul_f32 v[118:119], v[116:117], v[44:45]
	s_waitcnt lgkmcnt(2)
	v_pk_mul_f32 v[120:121], v[2:3], v[48:49]
	v_pk_fma_f32 v[118:119], v[114:115], v[42:43], v[118:119]
	v_pk_fma_f32 v[120:121], v[0:1], v[46:47], v[120:121]
	v_add_f32_e32 v122, v118, v119
	v_add_f32_e32 v123, v120, v121
	s_nop 0
	v_add_f32_dpp v122, v122, v122 quad_perm:[1,0,3,2] row_mask:0xf bank_mask:0xf bound_ctrl:1
	v_add_f32_dpp v123, v123, v123 quad_perm:[1,0,3,2] row_mask:0xf bank_mask:0xf bound_ctrl:1
	v_cndmask_b32_e32 v124, v123, v122, vcc
	s_nop 0
	s_nop 0
	v_add_f32_dpp v124, v124, v124 row_ror:2 row_mask:0xf bank_mask:0xf bound_ctrl:1
	s_nop 0
	s_nop 0
	v_add_f32_dpp v124, v124, v124 row_ror:4 row_mask:0xf bank_mask:0xf bound_ctrl:1
	s_nop 0
	s_nop 0
	v_add_f32_dpp v124, v124, v124 row_ror:8 row_mask:0xf bank_mask:0xf bound_ctrl:1
	ds_write_b32 v6, v124 offset:1920
	s_add_i32 s4, s4, 1
	s_cmpk_eq_i32 s4, 0x101
	s_waitcnt lgkmcnt(0)
	s_barrier
	s_cbranch_scc0 .LBB0_786
	s_setprio 0
